# SwiGLU epilogue: fold 1+e and the rs^2 multiply into one fma before the rcp (2 fewer packed ops per quad); bf16 GEMMs: first wait of each tile's first k-iteration lets 16 epilogue stores stay in fligh
# baseline (speedup 1.0000x reference)
; __device__ __forceinline__ float silu_f(float x) { return x * __builtin_amdgcn_rcpf(1.0f + __builtin_amdgcn_exp2f(-1.4426950408889634f * x)); }
;     __device__ __forceinline__ void operator()(const i32x4 (&acc)[2][2][4][2], const pg8::Unit& u, int wr, int wc, int fr_, int fq_, int tid) {
;     ...
;         for (int ai = 0; ai < 2; ++ai)
; #pragma unroll
;             for (int m = 0; m < 4; ++m) {
;                 const int row = row0 + ai * 128 + m * 16;
;                 const float rs = rsl[wr * 64 + fr + ai * 128 + m * 16];
;                 f32x4 h[2];
; #pragma unroll
;                 for (int n = 0; n < 2; ++n) {
; #pragma unroll
;                     for (int i = 0; i < 4; ++i) { const float g = (float)acc[ai][0][m][n][i] * (rs * cs[0][n][i]), up = (float)acc[ai][1][m][n][i] * (rs * cs[1][n][i]); h[n][i] = silu_f(g) * up; } }
;                 *(u32x4*)(H + ((size_t)(u.pm * (DFF / 64) + (col0 >> 6)) * 256 + (size_t)(row & 255)) * 64 + (col0 & 63)) = pack8bf(h[0], h[1]);
.LBB0_166:
	s_mul_i32 s13, s20, 0x58
	v_lshrrev_b32_e32 v175, 4, v195
	v_and_b32_e32 v174, 15, v195
	s_lshr_b32 s22, s21, 2
	s_lshl_b32 s22, s22, 10
	s_lshl_b32 s23, s41, 3
	s_add_i32 s22, s22, s23
	s_add_i32 s22, s22, 0x21000
	v_lshlrev_b32_e32 v176, 4, v175
	v_lshl_add_u32 v175, v175, 5, s22
	ds_read_b128 v[216:219], v175
	ds_read_b128 v[220:223], v175 offset:16
	ds_read_b128 v[224:227], v175 offset:128
	ds_read_b128 v[228:231], v175 offset:144
	v_add_u32_e32 v177, s40, v174
	v_lshl_add_u32 v174, v174, 2, s47
	ds_read_b32 v232, v174
	ds_read_b32 v234, v174 offset:64
	ds_read_b32 v236, v174 offset:128
	ds_read_b32 v238, v174 offset:192
	ds_read_b32 v240, v174 offset:512
	ds_read_b32 v242, v174 offset:576
	ds_read_b32 v244, v174 offset:640
	ds_read_b32 v246, v174 offset:704
	v_lshl_add_u32 v176, v177, 7, v176
	s_lshl_b32 s22, s21, 1
	s_add_i32 s13, s13, s22
	s_lshr_b32 s22, s41, 6
	s_add_i32 s13, s13, s22
	s_and_b32 s22, s41, 32
	s_lshl_b32 s22, s22, 1
	v_add_u32_e32 v176, s22, v176
	s_lshl_b32 s13, s13, 15
	s_add_u32 s20, s8, s13
	s_addc_u32 s21, s9, 0
	v_cvt_f32_i32_e32 v126, v126
	v_cvt_f32_i32_e32 v127, v127
	v_cvt_f32_i32_e32 v128, v128
	v_cvt_f32_i32_e32 v129, v129
	v_cvt_f32_i32_e32 v122, v122
	v_cvt_f32_i32_e32 v123, v123
	v_cvt_f32_i32_e32 v124, v124
	v_cvt_f32_i32_e32 v125, v125
	v_cvt_f32_i32_e32 v118, v118
	v_cvt_f32_i32_e32 v119, v119
	v_cvt_f32_i32_e32 v120, v120
	v_cvt_f32_i32_e32 v121, v121
	v_cvt_f32_i32_e32 v114, v114
	v_cvt_f32_i32_e32 v115, v115
	v_cvt_f32_i32_e32 v116, v116
	v_cvt_f32_i32_e32 v117, v117
	v_cvt_f32_i32_e32 v110, v110
	v_cvt_f32_i32_e32 v111, v111
	v_cvt_f32_i32_e32 v112, v112
	v_cvt_f32_i32_e32 v113, v113
	v_cvt_f32_i32_e32 v106, v106
	v_cvt_f32_i32_e32 v107, v107
	v_cvt_f32_i32_e32 v108, v108
	v_cvt_f32_i32_e32 v109, v109
	v_cvt_f32_i32_e32 v102, v102
	v_cvt_f32_i32_e32 v103, v103
	v_cvt_f32_i32_e32 v104, v104
	v_cvt_f32_i32_e32 v105, v105
	v_cvt_f32_i32_e32 v98, v98
	v_cvt_f32_i32_e32 v99, v99
	v_cvt_f32_i32_e32 v100, v100
	v_cvt_f32_i32_e32 v101, v101
	s_waitcnt lgkmcnt(0)
	v_mul_f32_e32 v233, v232, v232
	v_mul_f32_e32 v235, v234, v234
	v_mul_f32_e32 v237, v236, v236
	v_mul_f32_e32 v239, v238, v238
	v_mul_f32_e32 v241, v240, v240
	v_mul_f32_e32 v243, v242, v242
	v_mul_f32_e32 v245, v244, v244
	v_mul_f32_e32 v247, v246, v246
	v_rcp_f32_e32 v233, v233
	v_rcp_f32_e32 v235, v235
	v_rcp_f32_e32 v237, v237
	v_rcp_f32_e32 v239, v239
	v_rcp_f32_e32 v241, v241
	v_rcp_f32_e32 v243, v243
	v_rcp_f32_e32 v245, v245
	v_rcp_f32_e32 v247, v247
	v_mul_f32_e32 v232, 0xbfb8aa3b, v232
	v_mul_f32_e32 v234, 0xbfb8aa3b, v234
	v_mul_f32_e32 v236, 0xbfb8aa3b, v236
	v_mul_f32_e32 v238, 0xbfb8aa3b, v238
	v_mul_f32_e32 v240, 0xbfb8aa3b, v240
	v_mul_f32_e32 v242, 0xbfb8aa3b, v242
	v_mul_f32_e32 v244, 0xbfb8aa3b, v244
	v_mul_f32_e32 v246, 0xbfb8aa3b, v246
	v_cvt_f32_i32_e32 v94, v94
	v_cvt_f32_i32_e32 v95, v95
	v_cvt_f32_i32_e32 v96, v96
	v_cvt_f32_i32_e32 v97, v97
	v_cvt_f32_i32_e32 v90, v90
	v_cvt_f32_i32_e32 v91, v91
	v_cvt_f32_i32_e32 v92, v92
	v_cvt_f32_i32_e32 v93, v93
	v_cvt_f32_i32_e32 v86, v86
	v_cvt_f32_i32_e32 v87, v87
	v_cvt_f32_i32_e32 v88, v88
	v_cvt_f32_i32_e32 v89, v89
	v_cvt_f32_i32_e32 v82, v82
	v_cvt_f32_i32_e32 v83, v83
	v_cvt_f32_i32_e32 v84, v84
	v_cvt_f32_i32_e32 v85, v85
	v_pk_mul_f32 v[126:127], v[126:127], v[216:217]
	v_pk_mul_f32 v[128:129], v[128:129], v[218:219]
	v_pk_mul_f32 v[122:123], v[122:123], v[224:225]
	v_pk_mul_f32 v[124:125], v[124:125], v[226:227]
	v_pk_mul_f32 v[248:249], v[126:127], v[232:233] op_sel_hi:[1,0]
	v_pk_mul_f32 v[250:251], v[128:129], v[232:233] op_sel_hi:[1,0]
	v_pk_mul_f32 v[126:127], v[126:127], v[122:123]
	v_exp_f32_e32 v248, v248
	v_exp_f32_e32 v249, v249
	v_exp_f32_e32 v250, v250
	v_exp_f32_e32 v251, v251
	v_pk_mul_f32 v[128:129], v[128:129], v[124:125]
	v_pk_fma_f32 v[248:249], v[248:249], v[232:233], v[232:233] op_sel:[0,1,1] op_sel_hi:[1,1,1]
	v_pk_fma_f32 v[250:251], v[250:251], v[232:233], v[232:233] op_sel:[0,1,1] op_sel_hi:[1,1,1]
	v_rcp_f32_e32 v248, v248
	v_rcp_f32_e32 v249, v249
	v_rcp_f32_e32 v250, v250
	v_rcp_f32_e32 v251, v251
	v_pk_mul_f32 v[126:127], v[126:127], v[248:249]
	v_pk_mul_f32 v[128:129], v[128:129], v[250:251]
	v_cvt_pk_bf16_f32 v122, v126, v127
	v_cvt_pk_bf16_f32 v123, v128, v129
	v_pk_mul_f32 v[118:119], v[118:119], v[220:221]
	v_pk_mul_f32 v[120:121], v[120:121], v[222:223]
	v_pk_mul_f32 v[114:115], v[114:115], v[228:229]
	v_pk_mul_f32 v[116:117], v[116:117], v[230:231]
	v_pk_mul_f32 v[248:249], v[118:119], v[232:233] op_sel_hi:[1,0]
	v_pk_mul_f32 v[250:251], v[120:121], v[232:233] op_sel_hi:[1,0]
	v_pk_mul_f32 v[118:119], v[118:119], v[114:115]
	v_exp_f32_e32 v248, v248
	v_exp_f32_e32 v249, v249
	v_exp_f32_e32 v250, v250
	v_exp_f32_e32 v251, v251
	v_pk_mul_f32 v[120:121], v[120:121], v[116:117]
	v_pk_fma_f32 v[248:249], v[248:249], v[232:233], v[232:233] op_sel:[0,1,1] op_sel_hi:[1,1,1]
	v_pk_fma_f32 v[250:251], v[250:251], v[232:233], v[232:233] op_sel:[0,1,1] op_sel_hi:[1,1,1]
	v_rcp_f32_e32 v248, v248
	v_rcp_f32_e32 v249, v249
	v_rcp_f32_e32 v250, v250
	v_rcp_f32_e32 v251, v251
	v_pk_mul_f32 v[118:119], v[118:119], v[248:249]
	v_pk_mul_f32 v[120:121], v[120:121], v[250:251]
	v_cvt_pk_bf16_f32 v124, v118, v119
	v_cvt_pk_bf16_f32 v125, v120, v121
	s_mov_b64 s[22:23], s[20:21]
	global_store_dwordx4 v176, v[122:125], s[22:23] sc1
	v_cvt_f32_i32_e32 v78, v78
	v_cvt_f32_i32_e32 v79, v79
	v_cvt_f32_i32_e32 v80, v80
	v_cvt_f32_i32_e32 v81, v81
	v_cvt_f32_i32_e32 v74, v74
	v_cvt_f32_i32_e32 v75, v75
	v_cvt_f32_i32_e32 v76, v76
	v_cvt_f32_i32_e32 v77, v77
	v_cvt_f32_i32_e32 v70, v70
	v_cvt_f32_i32_e32 v71, v71
	v_cvt_f32_i32_e32 v72, v72
; __device__ __forceinline__ float silu_f(float x) { return x * __builtin_amdgcn_rcpf(1.0f + __builtin_amdgcn_exp2f(-1.4426950408889634f * x)); }
;     __device__ __forceinline__ void operator()(const i32x4 (&acc)[2][2][4][2], const pg8::Unit& u, int wr, int wc, int fr_, int fq_, int tid) {
;     ...
;         for (int ai = 0; ai < 2; ++ai)
; #pragma unroll
;             for (int m = 0; m < 4; ++m) {
;                 const int row = row0 + ai * 128 + m * 16;
;                 const float rs = rsl[wr * 64 + fr + ai * 128 + m * 16];
;                 f32x4 h[2];
; #pragma unroll
;                 for (int n = 0; n < 2; ++n) {
; #pragma unroll
;                     for (int i = 0; i < 4; ++i) { const float g = (float)acc[ai][0][m][n][i] * (rs * cs[0][n][i]), up = (float)acc[ai][1][m][n][i] * (rs * cs[1][n][i]); h[n][i] = silu_f(g) * up; } }
;                 *(u32x4*)(H + ((size_t)(u.pm * (DFF / 64) + (col0 >> 6)) * 256 + (size_t)(row & 255)) * 64 + (col0 & 63)) = pack8bf(h[0], h[1]);
	v_cvt_f32_i32_e32 v73, v73
	v_cvt_f32_i32_e32 v66, v66
	v_cvt_f32_i32_e32 v67, v67
	v_cvt_f32_i32_e32 v68, v68
	v_cvt_f32_i32_e32 v69, v69
	v_pk_mul_f32 v[110:111], v[110:111], v[216:217]
	v_pk_mul_f32 v[112:113], v[112:113], v[218:219]
	v_pk_mul_f32 v[106:107], v[106:107], v[224:225]
	v_pk_mul_f32 v[108:109], v[108:109], v[226:227]
	v_pk_mul_f32 v[248:249], v[110:111], v[234:235] op_sel_hi:[1,0]
	v_pk_mul_f32 v[250:251], v[112:113], v[234:235] op_sel_hi:[1,0]
	v_pk_mul_f32 v[110:111], v[110:111], v[106:107]
	v_exp_f32_e32 v248, v248
	v_exp_f32_e32 v249, v249
	v_exp_f32_e32 v250, v250
	v_exp_f32_e32 v251, v251
	v_pk_mul_f32 v[112:113], v[112:113], v[108:109]
	v_pk_fma_f32 v[248:249], v[248:249], v[234:235], v[234:235] op_sel:[0,1,1] op_sel_hi:[1,1,1]
	v_pk_fma_f32 v[250:251], v[250:251], v[234:235], v[234:235] op_sel:[0,1,1] op_sel_hi:[1,1,1]
	v_rcp_f32_e32 v248, v248
	v_rcp_f32_e32 v249, v249
	v_rcp_f32_e32 v250, v250
	v_rcp_f32_e32 v251, v251
	v_pk_mul_f32 v[110:111], v[110:111], v[248:249]
	v_pk_mul_f32 v[112:113], v[112:113], v[250:251]
	v_cvt_pk_bf16_f32 v106, v110, v111
	v_cvt_pk_bf16_f32 v107, v112, v113
	v_pk_mul_f32 v[102:103], v[102:103], v[220:221]
	v_pk_mul_f32 v[104:105], v[104:105], v[222:223]
	v_pk_mul_f32 v[98:99], v[98:99], v[228:229]
	v_pk_mul_f32 v[100:101], v[100:101], v[230:231]
	v_pk_mul_f32 v[248:249], v[102:103], v[234:235] op_sel_hi:[1,0]
	v_pk_mul_f32 v[250:251], v[104:105], v[234:235] op_sel_hi:[1,0]
	v_pk_mul_f32 v[102:103], v[102:103], v[98:99]
	v_exp_f32_e32 v248, v248
	v_exp_f32_e32 v249, v249
	v_exp_f32_e32 v250, v250
	v_exp_f32_e32 v251, v251
	v_pk_mul_f32 v[104:105], v[104:105], v[100:101]
	v_pk_fma_f32 v[248:249], v[248:249], v[234:235], v[234:235] op_sel:[0,1,1] op_sel_hi:[1,1,1]
	v_pk_fma_f32 v[250:251], v[250:251], v[234:235], v[234:235] op_sel:[0,1,1] op_sel_hi:[1,1,1]
	v_rcp_f32_e32 v248, v248
	v_rcp_f32_e32 v249, v249
	v_rcp_f32_e32 v250, v250
	v_rcp_f32_e32 v251, v251
	v_pk_mul_f32 v[102:103], v[102:103], v[248:249]
	v_pk_mul_f32 v[104:105], v[104:105], v[250:251]
	v_cvt_pk_bf16_f32 v108, v102, v103
	v_cvt_pk_bf16_f32 v109, v104, v105
	global_store_dwordx4 v176, v[106:109], s[22:23] offset:2048 sc1
	v_cvt_f32_i32_e32 v62, v62
	v_cvt_f32_i32_e32 v63, v63
	v_cvt_f32_i32_e32 v64, v64
	v_cvt_f32_i32_e32 v65, v65
	v_cvt_f32_i32_e32 v58, v58
	v_cvt_f32_i32_e32 v59, v59
	v_cvt_f32_i32_e32 v60, v60
	v_cvt_f32_i32_e32 v61, v61
	v_cvt_f32_i32_e32 v54, v54
	v_cvt_f32_i32_e32 v55, v55
	v_cvt_f32_i32_e32 v56, v56
	v_cvt_f32_i32_e32 v57, v57
	v_cvt_f32_i32_e32 v50, v50
	v_cvt_f32_i32_e32 v51, v51
	v_cvt_f32_i32_e32 v52, v52
	v_cvt_f32_i32_e32 v53, v53
	v_pk_mul_f32 v[94:95], v[94:95], v[216:217]
	v_pk_mul_f32 v[96:97], v[96:97], v[218:219]
	v_pk_mul_f32 v[90:91], v[90:91], v[224:225]
	v_pk_mul_f32 v[92:93], v[92:93], v[226:227]
	v_pk_mul_f32 v[248:249], v[94:95], v[236:237] op_sel_hi:[1,0]
	v_pk_mul_f32 v[250:251], v[96:97], v[236:237] op_sel_hi:[1,0]
	v_pk_mul_f32 v[94:95], v[94:95], v[90:91]
	v_exp_f32_e32 v248, v248
	v_exp_f32_e32 v249, v249
	v_exp_f32_e32 v250, v250
	v_exp_f32_e32 v251, v251
	v_pk_mul_f32 v[96:97], v[96:97], v[92:93]
	v_pk_fma_f32 v[248:249], v[248:249], v[236:237], v[236:237] op_sel:[0,1,1] op_sel_hi:[1,1,1]
	v_pk_fma_f32 v[250:251], v[250:251], v[236:237], v[236:237] op_sel:[0,1,1] op_sel_hi:[1,1,1]
	v_rcp_f32_e32 v248, v248
	v_rcp_f32_e32 v249, v249
	v_rcp_f32_e32 v250, v250
	v_rcp_f32_e32 v251, v251
	v_pk_mul_f32 v[94:95], v[94:95], v[248:249]
	v_pk_mul_f32 v[96:97], v[96:97], v[250:251]
	v_cvt_pk_bf16_f32 v90, v94, v95
	v_cvt_pk_bf16_f32 v91, v96, v97
	v_pk_mul_f32 v[86:87], v[86:87], v[220:221]
	v_pk_mul_f32 v[88:89], v[88:89], v[222:223]
	v_pk_mul_f32 v[82:83], v[82:83], v[228:229]
	v_pk_mul_f32 v[84:85], v[84:85], v[230:231]
	v_pk_mul_f32 v[248:249], v[86:87], v[236:237] op_sel_hi:[1,0]
	v_pk_mul_f32 v[250:251], v[88:89], v[236:237] op_sel_hi:[1,0]
	v_pk_mul_f32 v[86:87], v[86:87], v[82:83]
	v_exp_f32_e32 v248, v248
	v_exp_f32_e32 v249, v249
	v_exp_f32_e32 v250, v250
	v_exp_f32_e32 v251, v251
	v_pk_mul_f32 v[88:89], v[88:89], v[84:85]
	v_pk_fma_f32 v[248:249], v[248:249], v[236:237], v[236:237] op_sel:[0,1,1] op_sel_hi:[1,1,1]
	v_pk_fma_f32 v[250:251], v[250:251], v[236:237], v[236:237] op_sel:[0,1,1] op_sel_hi:[1,1,1]
	v_rcp_f32_e32 v248, v248
	v_rcp_f32_e32 v249, v249
	v_rcp_f32_e32 v250, v250
	v_rcp_f32_e32 v251, v251
	v_pk_mul_f32 v[86:87], v[86:87], v[248:249]
	v_pk_mul_f32 v[88:89], v[88:89], v[250:251]
	v_cvt_pk_bf16_f32 v92, v86, v87
	v_cvt_pk_bf16_f32 v93, v88, v89
	s_add_u32 s22, s20, 0x1000
	s_addc_u32 s23, s21, 0
	global_store_dwordx4 v176, v[90:93], s[22:23] sc1
	v_cvt_f32_i32_e32 v46, v46
	v_cvt_f32_i32_e32 v47, v47
	v_cvt_f32_i32_e32 v48, v48
	v_cvt_f32_i32_e32 v49, v49
	v_cvt_f32_i32_e32 v42, v42
	v_cvt_f32_i32_e32 v43, v43
	v_cvt_f32_i32_e32 v44, v44
	v_cvt_f32_i32_e32 v45, v45
	v_cvt_f32_i32_e32 v38, v38
	v_cvt_f32_i32_e32 v39, v39
	v_cvt_f32_i32_e32 v40, v40
	v_cvt_f32_i32_e32 v41, v41
	v_cvt_f32_i32_e32 v34, v34
	v_cvt_f32_i32_e32 v35, v35
	v_cvt_f32_i32_e32 v36, v36
	v_cvt_f32_i32_e32 v37, v37
	v_pk_mul_f32 v[78:79], v[78:79], v[216:217]
	v_pk_mul_f32 v[80:81], v[80:81], v[218:219]
	v_pk_mul_f32 v[74:75], v[74:75], v[224:225]
	v_pk_mul_f32 v[76:77], v[76:77], v[226:227]
	v_pk_mul_f32 v[248:249], v[78:79], v[238:239] op_sel_hi:[1,0]
	v_pk_mul_f32 v[250:251], v[80:81], v[238:239] op_sel_hi:[1,0]
	v_pk_mul_f32 v[78:79], v[78:79], v[74:75]
	v_exp_f32_e32 v248, v248
	v_exp_f32_e32 v249, v249
	v_exp_f32_e32 v250, v250
	v_exp_f32_e32 v251, v251
	v_pk_mul_f32 v[80:81], v[80:81], v[76:77]
	v_pk_fma_f32 v[248:249], v[248:249], v[238:239], v[238:239] op_sel:[0,1,1] op_sel_hi:[1,1,1]
; __device__ __forceinline__ float silu_f(float x) { return x * __builtin_amdgcn_rcpf(1.0f + __builtin_amdgcn_exp2f(-1.4426950408889634f * x)); }
;     __device__ __forceinline__ void operator()(const i32x4 (&acc)[2][2][4][2], const pg8::Unit& u, int wr, int wc, int fr_, int fq_, int tid) {
;     ...
;         for (int ai = 0; ai < 2; ++ai)
; #pragma unroll
;             for (int m = 0; m < 4; ++m) {
;                 const int row = row0 + ai * 128 + m * 16;
;                 const float rs = rsl[wr * 64 + fr + ai * 128 + m * 16];
;                 f32x4 h[2];
; #pragma unroll
;                 for (int n = 0; n < 2; ++n) {
; #pragma unroll
;                     for (int i = 0; i < 4; ++i) { const float g = (float)acc[ai][0][m][n][i] * (rs * cs[0][n][i]), up = (float)acc[ai][1][m][n][i] * (rs * cs[1][n][i]); h[n][i] = silu_f(g) * up; } }
;                 *(u32x4*)(H + ((size_t)(u.pm * (DFF / 64) + (col0 >> 6)) * 256 + (size_t)(row & 255)) * 64 + (col0 & 63)) = pack8bf(h[0], h[1]);
	v_pk_fma_f32 v[250:251], v[250:251], v[238:239], v[238:239] op_sel:[0,1,1] op_sel_hi:[1,1,1]
	v_rcp_f32_e32 v248, v248
	v_rcp_f32_e32 v249, v249
	v_rcp_f32_e32 v250, v250
	v_rcp_f32_e32 v251, v251
	v_pk_mul_f32 v[78:79], v[78:79], v[248:249]
	v_pk_mul_f32 v[80:81], v[80:81], v[250:251]
	v_cvt_pk_bf16_f32 v74, v78, v79
	v_cvt_pk_bf16_f32 v75, v80, v81
	v_pk_mul_f32 v[70:71], v[70:71], v[220:221]
	v_pk_mul_f32 v[72:73], v[72:73], v[222:223]
	v_pk_mul_f32 v[66:67], v[66:67], v[228:229]
	v_pk_mul_f32 v[68:69], v[68:69], v[230:231]
	v_pk_mul_f32 v[248:249], v[70:71], v[238:239] op_sel_hi:[1,0]
	v_pk_mul_f32 v[250:251], v[72:73], v[238:239] op_sel_hi:[1,0]
	v_pk_mul_f32 v[70:71], v[70:71], v[66:67]
	v_exp_f32_e32 v248, v248
	v_exp_f32_e32 v249, v249
	v_exp_f32_e32 v250, v250
	v_exp_f32_e32 v251, v251
	v_pk_mul_f32 v[72:73], v[72:73], v[68:69]
	v_pk_fma_f32 v[248:249], v[248:249], v[238:239], v[238:239] op_sel:[0,1,1] op_sel_hi:[1,1,1]
	v_pk_fma_f32 v[250:251], v[250:251], v[238:239], v[238:239] op_sel:[0,1,1] op_sel_hi:[1,1,1]
	v_rcp_f32_e32 v248, v248
	v_rcp_f32_e32 v249, v249
	v_rcp_f32_e32 v250, v250
	v_rcp_f32_e32 v251, v251
	v_pk_mul_f32 v[70:71], v[70:71], v[248:249]
	v_pk_mul_f32 v[72:73], v[72:73], v[250:251]
	v_cvt_pk_bf16_f32 v76, v70, v71
	v_cvt_pk_bf16_f32 v77, v72, v73
	global_store_dwordx4 v176, v[74:77], s[22:23] offset:2048 sc1
	v_cvt_f32_i32_e32 v30, v30
	v_cvt_f32_i32_e32 v31, v31
	v_cvt_f32_i32_e32 v32, v32
	v_cvt_f32_i32_e32 v33, v33
	v_cvt_f32_i32_e32 v26, v26
	v_cvt_f32_i32_e32 v27, v27
	v_cvt_f32_i32_e32 v28, v28
	v_cvt_f32_i32_e32 v29, v29
	v_cvt_f32_i32_e32 v22, v22
	v_cvt_f32_i32_e32 v23, v23
	v_cvt_f32_i32_e32 v24, v24
	v_cvt_f32_i32_e32 v25, v25
	v_cvt_f32_i32_e32 v18, v18
	v_cvt_f32_i32_e32 v19, v19
	v_cvt_f32_i32_e32 v20, v20
	v_cvt_f32_i32_e32 v21, v21
	v_pk_mul_f32 v[62:63], v[62:63], v[216:217]
	v_pk_mul_f32 v[64:65], v[64:65], v[218:219]
	v_pk_mul_f32 v[58:59], v[58:59], v[224:225]
	v_pk_mul_f32 v[60:61], v[60:61], v[226:227]
	v_pk_mul_f32 v[248:249], v[62:63], v[240:241] op_sel_hi:[1,0]
	v_pk_mul_f32 v[250:251], v[64:65], v[240:241] op_sel_hi:[1,0]
	v_pk_mul_f32 v[62:63], v[62:63], v[58:59]
	v_exp_f32_e32 v248, v248
	v_exp_f32_e32 v249, v249
	v_exp_f32_e32 v250, v250
	v_exp_f32_e32 v251, v251
	v_pk_mul_f32 v[64:65], v[64:65], v[60:61]
	v_pk_fma_f32 v[248:249], v[248:249], v[240:241], v[240:241] op_sel:[0,1,1] op_sel_hi:[1,1,1]
	v_pk_fma_f32 v[250:251], v[250:251], v[240:241], v[240:241] op_sel:[0,1,1] op_sel_hi:[1,1,1]
	v_rcp_f32_e32 v248, v248
	v_rcp_f32_e32 v249, v249
	v_rcp_f32_e32 v250, v250
	v_rcp_f32_e32 v251, v251
	v_pk_mul_f32 v[62:63], v[62:63], v[248:249]
	v_pk_mul_f32 v[64:65], v[64:65], v[250:251]
	v_cvt_pk_bf16_f32 v58, v62, v63
	v_cvt_pk_bf16_f32 v59, v64, v65
	v_pk_mul_f32 v[54:55], v[54:55], v[220:221]
	v_pk_mul_f32 v[56:57], v[56:57], v[222:223]
	v_pk_mul_f32 v[50:51], v[50:51], v[228:229]
	v_pk_mul_f32 v[52:53], v[52:53], v[230:231]
	v_pk_mul_f32 v[248:249], v[54:55], v[240:241] op_sel_hi:[1,0]
	v_pk_mul_f32 v[250:251], v[56:57], v[240:241] op_sel_hi:[1,0]
	v_pk_mul_f32 v[54:55], v[54:55], v[50:51]
	v_exp_f32_e32 v248, v248
	v_exp_f32_e32 v249, v249
	v_exp_f32_e32 v250, v250
	v_exp_f32_e32 v251, v251
	v_pk_mul_f32 v[56:57], v[56:57], v[52:53]
	v_pk_fma_f32 v[248:249], v[248:249], v[240:241], v[240:241] op_sel:[0,1,1] op_sel_hi:[1,1,1]
	v_pk_fma_f32 v[250:251], v[250:251], v[240:241], v[240:241] op_sel:[0,1,1] op_sel_hi:[1,1,1]
	v_rcp_f32_e32 v248, v248
	v_rcp_f32_e32 v249, v249
	v_rcp_f32_e32 v250, v250
	v_rcp_f32_e32 v251, v251
	v_pk_mul_f32 v[54:55], v[54:55], v[248:249]
	v_pk_mul_f32 v[56:57], v[56:57], v[250:251]
	v_cvt_pk_bf16_f32 v60, v54, v55
	v_cvt_pk_bf16_f32 v61, v56, v57
	s_add_u32 s22, s20, 0x4000
	s_addc_u32 s23, s21, 0
	global_store_dwordx4 v176, v[58:61], s[22:23] sc1
	v_cvt_f32_i32_e32 v14, v14
	v_cvt_f32_i32_e32 v15, v15
	v_cvt_f32_i32_e32 v16, v16
	v_cvt_f32_i32_e32 v17, v17
	v_cvt_f32_i32_e32 v10, v10
	v_cvt_f32_i32_e32 v11, v11
	v_cvt_f32_i32_e32 v12, v12
	v_cvt_f32_i32_e32 v13, v13
	v_cvt_f32_i32_e32 v6, v6
	v_cvt_f32_i32_e32 v7, v7
	v_cvt_f32_i32_e32 v8, v8
	v_cvt_f32_i32_e32 v9, v9
	v_cvt_f32_i32_e32 v2, v2
	v_cvt_f32_i32_e32 v3, v3
	v_cvt_f32_i32_e32 v4, v4
	v_cvt_f32_i32_e32 v5, v5
	v_pk_mul_f32 v[46:47], v[46:47], v[216:217]
	v_pk_mul_f32 v[48:49], v[48:49], v[218:219]
	v_pk_mul_f32 v[42:43], v[42:43], v[224:225]
	v_pk_mul_f32 v[44:45], v[44:45], v[226:227]
	v_pk_mul_f32 v[248:249], v[46:47], v[242:243] op_sel_hi:[1,0]
	v_pk_mul_f32 v[250:251], v[48:49], v[242:243] op_sel_hi:[1,0]
	v_pk_mul_f32 v[46:47], v[46:47], v[42:43]
	v_exp_f32_e32 v248, v248
	v_exp_f32_e32 v249, v249
	v_exp_f32_e32 v250, v250
	v_exp_f32_e32 v251, v251
	v_pk_mul_f32 v[48:49], v[48:49], v[44:45]
	v_pk_fma_f32 v[248:249], v[248:249], v[242:243], v[242:243] op_sel:[0,1,1] op_sel_hi:[1,1,1]
	v_pk_fma_f32 v[250:251], v[250:251], v[242:243], v[242:243] op_sel:[0,1,1] op_sel_hi:[1,1,1]
	v_rcp_f32_e32 v248, v248
	v_rcp_f32_e32 v249, v249
	v_rcp_f32_e32 v250, v250
	v_rcp_f32_e32 v251, v251
	v_pk_mul_f32 v[46:47], v[46:47], v[248:249]
	v_pk_mul_f32 v[48:49], v[48:49], v[250:251]
; __device__ __forceinline__ float silu_f(float x) { return x * __builtin_amdgcn_rcpf(1.0f + __builtin_amdgcn_exp2f(-1.4426950408889634f * x)); }
;     __device__ __forceinline__ void operator()(const i32x4 (&acc)[2][2][4][2], const pg8::Unit& u, int wr, int wc, int fr_, int fq_, int tid) {
;     ...
;         for (int ai = 0; ai < 2; ++ai)
; #pragma unroll
;             for (int m = 0; m < 4; ++m) {
;                 const int row = row0 + ai * 128 + m * 16;
;                 const float rs = rsl[wr * 64 + fr + ai * 128 + m * 16];
;                 f32x4 h[2];
; #pragma unroll
;                 for (int n = 0; n < 2; ++n) {
; #pragma unroll
;                     for (int i = 0; i < 4; ++i) { const float g = (float)acc[ai][0][m][n][i] * (rs * cs[0][n][i]), up = (float)acc[ai][1][m][n][i] * (rs * cs[1][n][i]); h[n][i] = silu_f(g) * up; } }
;                 *(u32x4*)(H + ((size_t)(u.pm * (DFF / 64) + (col0 >> 6)) * 256 + (size_t)(row & 255)) * 64 + (col0 & 63)) = pack8bf(h[0], h[1]);
	v_cvt_pk_bf16_f32 v42, v46, v47
	v_cvt_pk_bf16_f32 v43, v48, v49
	v_pk_mul_f32 v[38:39], v[38:39], v[220:221]
	v_pk_mul_f32 v[40:41], v[40:41], v[222:223]
	v_pk_mul_f32 v[34:35], v[34:35], v[228:229]
	v_pk_mul_f32 v[36:37], v[36:37], v[230:231]
	v_pk_mul_f32 v[248:249], v[38:39], v[242:243] op_sel_hi:[1,0]
	v_pk_mul_f32 v[250:251], v[40:41], v[242:243] op_sel_hi:[1,0]
	v_pk_mul_f32 v[38:39], v[38:39], v[34:35]
	v_exp_f32_e32 v248, v248
	v_exp_f32_e32 v249, v249
	v_exp_f32_e32 v250, v250
	v_exp_f32_e32 v251, v251
	v_pk_mul_f32 v[40:41], v[40:41], v[36:37]
	v_pk_fma_f32 v[248:249], v[248:249], v[242:243], v[242:243] op_sel:[0,1,1] op_sel_hi:[1,1,1]
	v_pk_fma_f32 v[250:251], v[250:251], v[242:243], v[242:243] op_sel:[0,1,1] op_sel_hi:[1,1,1]
	v_rcp_f32_e32 v248, v248
	v_rcp_f32_e32 v249, v249
	v_rcp_f32_e32 v250, v250
	v_rcp_f32_e32 v251, v251
	v_pk_mul_f32 v[38:39], v[38:39], v[248:249]
	v_pk_mul_f32 v[40:41], v[40:41], v[250:251]
	v_cvt_pk_bf16_f32 v44, v38, v39
	v_cvt_pk_bf16_f32 v45, v40, v41
	global_store_dwordx4 v176, v[42:45], s[22:23] offset:2048 sc1
	v_pk_mul_f32 v[30:31], v[30:31], v[216:217]
	v_pk_mul_f32 v[32:33], v[32:33], v[218:219]
	v_pk_mul_f32 v[26:27], v[26:27], v[224:225]
	v_pk_mul_f32 v[28:29], v[28:29], v[226:227]
	v_pk_mul_f32 v[248:249], v[30:31], v[244:245] op_sel_hi:[1,0]
	v_pk_mul_f32 v[250:251], v[32:33], v[244:245] op_sel_hi:[1,0]
	v_pk_mul_f32 v[30:31], v[30:31], v[26:27]
	v_exp_f32_e32 v248, v248
	v_exp_f32_e32 v249, v249
	v_exp_f32_e32 v250, v250
	v_exp_f32_e32 v251, v251
	v_pk_mul_f32 v[32:33], v[32:33], v[28:29]
	v_pk_fma_f32 v[248:249], v[248:249], v[244:245], v[244:245] op_sel:[0,1,1] op_sel_hi:[1,1,1]
	v_pk_fma_f32 v[250:251], v[250:251], v[244:245], v[244:245] op_sel:[0,1,1] op_sel_hi:[1,1,1]
	v_rcp_f32_e32 v248, v248
	v_rcp_f32_e32 v249, v249
	v_rcp_f32_e32 v250, v250
	v_rcp_f32_e32 v251, v251
	v_pk_mul_f32 v[30:31], v[30:31], v[248:249]
	v_pk_mul_f32 v[32:33], v[32:33], v[250:251]
	v_cvt_pk_bf16_f32 v26, v30, v31
	v_cvt_pk_bf16_f32 v27, v32, v33
	v_pk_mul_f32 v[22:23], v[22:23], v[220:221]
	v_pk_mul_f32 v[24:25], v[24:25], v[222:223]
	v_pk_mul_f32 v[18:19], v[18:19], v[228:229]
	v_pk_mul_f32 v[20:21], v[20:21], v[230:231]
	v_pk_mul_f32 v[248:249], v[22:23], v[244:245] op_sel_hi:[1,0]
	v_pk_mul_f32 v[250:251], v[24:25], v[244:245] op_sel_hi:[1,0]
	v_pk_mul_f32 v[22:23], v[22:23], v[18:19]
	v_exp_f32_e32 v248, v248
	v_exp_f32_e32 v249, v249
	v_exp_f32_e32 v250, v250
	v_exp_f32_e32 v251, v251
	v_pk_mul_f32 v[24:25], v[24:25], v[20:21]
	v_pk_fma_f32 v[248:249], v[248:249], v[244:245], v[244:245] op_sel:[0,1,1] op_sel_hi:[1,1,1]
	v_pk_fma_f32 v[250:251], v[250:251], v[244:245], v[244:245] op_sel:[0,1,1] op_sel_hi:[1,1,1]
	v_rcp_f32_e32 v248, v248
	v_rcp_f32_e32 v249, v249
	v_rcp_f32_e32 v250, v250
	v_rcp_f32_e32 v251, v251
	v_pk_mul_f32 v[22:23], v[22:23], v[248:249]
	v_pk_mul_f32 v[24:25], v[24:25], v[250:251]
	v_cvt_pk_bf16_f32 v28, v22, v23
	v_cvt_pk_bf16_f32 v29, v24, v25
	s_add_u32 s22, s20, 0x5000
	s_addc_u32 s23, s21, 0
	global_store_dwordx4 v176, v[26:29], s[22:23] sc1
	v_pk_mul_f32 v[14:15], v[14:15], v[216:217]
	v_pk_mul_f32 v[16:17], v[16:17], v[218:219]
	v_pk_mul_f32 v[10:11], v[10:11], v[224:225]
	v_pk_mul_f32 v[12:13], v[12:13], v[226:227]
	v_pk_mul_f32 v[248:249], v[14:15], v[246:247] op_sel_hi:[1,0]
	v_pk_mul_f32 v[250:251], v[16:17], v[246:247] op_sel_hi:[1,0]
	v_pk_mul_f32 v[14:15], v[14:15], v[10:11]
	v_exp_f32_e32 v248, v248
	v_exp_f32_e32 v249, v249
	v_exp_f32_e32 v250, v250
	v_exp_f32_e32 v251, v251
	v_pk_mul_f32 v[16:17], v[16:17], v[12:13]
	v_pk_fma_f32 v[248:249], v[248:249], v[246:247], v[246:247] op_sel:[0,1,1] op_sel_hi:[1,1,1]
	v_pk_fma_f32 v[250:251], v[250:251], v[246:247], v[246:247] op_sel:[0,1,1] op_sel_hi:[1,1,1]
	v_rcp_f32_e32 v248, v248
	v_rcp_f32_e32 v249, v249
	v_rcp_f32_e32 v250, v250
	v_rcp_f32_e32 v251, v251
	v_pk_mul_f32 v[14:15], v[14:15], v[248:249]
	v_pk_mul_f32 v[16:17], v[16:17], v[250:251]
	v_cvt_pk_bf16_f32 v10, v14, v15
	v_cvt_pk_bf16_f32 v11, v16, v17
	v_pk_mul_f32 v[6:7], v[6:7], v[220:221]
	v_pk_mul_f32 v[8:9], v[8:9], v[222:223]
	v_pk_mul_f32 v[2:3], v[2:3], v[228:229]
	v_pk_mul_f32 v[4:5], v[4:5], v[230:231]
	v_pk_mul_f32 v[248:249], v[6:7], v[246:247] op_sel_hi:[1,0]
	v_pk_mul_f32 v[250:251], v[8:9], v[246:247] op_sel_hi:[1,0]
	v_pk_mul_f32 v[6:7], v[6:7], v[2:3]
	v_exp_f32_e32 v248, v248
	v_exp_f32_e32 v249, v249
	v_exp_f32_e32 v250, v250
	v_exp_f32_e32 v251, v251
	v_pk_mul_f32 v[8:9], v[8:9], v[4:5]
	v_pk_fma_f32 v[248:249], v[248:249], v[246:247], v[246:247] op_sel:[0,1,1] op_sel_hi:[1,1,1]
	v_pk_fma_f32 v[250:251], v[250:251], v[246:247], v[246:247] op_sel:[0,1,1] op_sel_hi:[1,1,1]
	v_rcp_f32_e32 v248, v248
	v_rcp_f32_e32 v249, v249
	v_rcp_f32_e32 v250, v250
	v_rcp_f32_e32 v251, v251
	v_pk_mul_f32 v[6:7], v[6:7], v[248:249]
	v_pk_mul_f32 v[8:9], v[8:9], v[250:251]
	v_cvt_pk_bf16_f32 v12, v6, v7
	v_cvt_pk_bf16_f32 v13, v8, v9
	global_store_dwordx4 v176, v[10:13], s[22:23] offset:2048 sc1
	s_mov_b64 s[20:21], -1
	s_andn2_b64 vcc, exec, s[4:5]
	s_cbranch_vccnz .LBB0_159
	s_andn2_b64 vcc, exec, s[6:7]
	s_cbranch_vccnz .LBB0_158
	s_barrier
	s_branch .LBB0_158

; #define PG8_STAGE(bufoff, gbase, voff) do { _Pragma("unroll") for (int _i = 0; _i < 2; ++_i) \
;         __builtin_amdgcn_global_load_lds((const unsigned*)((const char*)(gbase) + (voff)[_i]), (PG8_LAS unsigned*)(lds + (bufoff) + ldsw + _i * 8192), 16, 0, 0); } while (0)
; #define PG8_LDA(dst, b, h) do { _Pragma("unroll") for (int m = 0; m < 4; ++m) _Pragma("unroll") for (int k = 0; k < 2; ++k) dst[m][k] = *(const PG8_LAS frag_t*)(lds + PG8_SA(b, h) + aoff + m * 2048 + k * 1024); } while (0)
; #define PG8_LDB(dst, b, h) do { _Pragma("unroll") for (int n = 0; n < 2; ++n) _Pragma("unroll") for (int k = 0; k < 2; ++k) dst[n][k] = *(const PG8_LAS frag_t*)(lds + PG8_SB(b, h) + boff + n * 2048 + k * 1024); } while (0)
; #define PG8_MMA(ai, bj, At, Bt) do { __builtin_amdgcn_s_setprio(1); _Pragma("unroll") for (int m = 0; m < 4; ++m) _Pragma("unroll") for (int n = 0; n < 2; ++n) _Pragma("unroll") for (int k = 0; k < 2; ++k) \
;         acc[ai][bj][m][n] = mma1v<MMAV>(Bt[n][k], At[m][k], acc[ai][bj][m][n]); __builtin_amdgcn_s_setprio(0); } while (0)
; #define PG8_WAIT_V(n) asm volatile("s_waitcnt vmcnt(" #n ")" ::: "memory")
; #define PG8_WAIT_L(n) asm volatile("s_waitcnt lgkmcnt(" #n ")" ::: "memory")
;     ...
;         const bool has_next = S.next(ui + 1, nxt);
;         const char* nA = has_next ? (const char*)g.A + (size_t)nxt.pm * tstep : cA; const char* nB = has_next ? (const char*)g.Bt + (size_t)nxt.pn * tstep : cB;
;         for (int t = 0; t < nt; t += 2) {
;             const bool last = (t == nt - 2);
;             const char* a1 = cA + (size_t)(t + 1) * kstep;
;             const char* a2 = last ? nA : cA + (size_t)(t + 2) * kstep; const char* b2 = last ? nB : cB + (size_t)(t + 2) * kstepB;
;             const char* a3 = a2 + kstep; const char* b3 = b2 + kstepB;
;             if (last && has_next) S.a_ready(nxt);
;             if constexpr (SP2) {
;             PG8_LDB(B0, 0, 0); PG8_LDB(B1, 0, 1); PG8_SCHED; PG8_LDA(At, 0, 0); PG8_STAGE(PG8_SA(1, 1), a1 + hstep, voffA);
;             PG8_WAIT_V(8); PG8_WAIT_L(0); PG8_BAR; PG8_MMA(0, 0, At, B0); PG8_MMA(0, 1, At, B1); PG8_BAR; PG8_SCHED;
;             PG8_LDA(At, 0, 1); PG8_STAGE(PG8_SB(0, 0), b2, voffB); PG8_STAGE(PG8_SB(0, 1), b2 + hstepB, voffB); PG8_STAGE(PG8_SA(0, 0), a2, voffA);
;             PG8_WAIT_V(8); PG8_WAIT_L(0); PG8_BAR; PG8_MMA(1, 0, At, B0); PG8_MMA(1, 1, At, B1); PG8_BAR; PG8_SCHED;
.LBB0_247:
	s_add_u32 s6, s24, 0xc000
	s_addc_u32 s7, s25, 0
	s_add_u32 s53, s8, 0x10000
	s_addc_u32 s54, s9, 0
	s_mov_b32 s55, -2
	s_waitcnt lgkmcnt(0)
	s_add_u32 s8, s6, 0x4000
	s_addc_u32 s9, s7, 0
	s_cmpk_eq_i32 s55, 0x54
	s_cselect_b32 s26, s20, s8
	s_cselect_b32 s27, s21, s9
	s_cselect_b32 s24, s22, s53
	s_cselect_b32 s25, s23, s54
	s_add_u32 s8, s26, 0x8000
	s_addc_u32 s9, s27, 0
	s_add_i32 s56, 0, 0x10000
	s_add_i32 s58, 0, 0x14000
	v_add_u32_e32 v142, s56, v216
	v_add_u32_e32 v158, s58, v216
	ds_read_b128 v[130:133], v142
	ds_read_b128 v[134:137], v142 offset:1024
	ds_read_b128 v[138:141], v142 offset:2048
	ds_read_b128 v[142:145], v142 offset:3072
	ds_read_b128 v[146:149], v158
	ds_read_b128 v[150:153], v158 offset:1024
	ds_read_b128 v[154:157], v158 offset:2048
	ds_read_b128 v[158:161], v158 offset:3072
	v_lshl_add_u64 v[242:243], s[6:7], 0, v[180:181]
	s_add_i32 m0, s37, 0xc000
	ds_read_b128 v[184:187], v217
	ds_read_b128 v[188:191], v217 offset:1024
	ds_read_b128 v[218:221], v217 offset:2048
	ds_read_b128 v[222:225], v217 offset:3072
	ds_read_b128 v[226:229], v217 offset:4096
	ds_read_b128 v[230:233], v217 offset:5120
	ds_read_b128 v[234:237], v217 offset:6144
	ds_read_b128 v[238:241], v217 offset:7168
	global_load_lds_dwordx4 v[242:243], off
	v_lshl_add_u64 v[242:243], s[6:7], 0, v[182:183]
	s_add_i32 m0, s37, 0xe000
	s_nop 0
	global_load_lds_dwordx4 v[242:243], off
	s_waitcnt vmcnt(24)
	s_waitcnt lgkmcnt(0)
	s_barrier
	s_setprio 1
	s_waitcnt lgkmcnt(0)
	v_mfma_f32_16x16x32_bf16 v[126:129], v[130:133], v[184:187], 0
	v_mfma_f32_16x16x32_bf16 v[122:125], v[138:141], v[184:187], 0
	v_mfma_f32_16x16x32_bf16 v[110:113], v[130:133], v[218:221], 0
	v_mfma_f32_16x16x32_bf16 v[106:109], v[138:141], v[218:221], 0
	v_mfma_f32_16x16x32_bf16 v[94:97], v[130:133], v[226:229], 0
	v_mfma_f32_16x16x32_bf16 v[90:93], v[138:141], v[226:229], 0
	v_mfma_f32_16x16x32_bf16 v[78:81], v[130:133], v[234:237], 0
	v_mfma_f32_16x16x32_bf16 v[74:77], v[138:141], v[234:237], 0
	v_mfma_f32_16x16x32_bf16 v[126:129], v[134:137], v[188:191], v[126:129]
	v_mfma_f32_16x16x32_bf16 v[122:125], v[142:145], v[188:191], v[122:125]
	v_mfma_f32_16x16x32_bf16 v[110:113], v[134:137], v[222:225], v[110:113]
	v_mfma_f32_16x16x32_bf16 v[106:109], v[142:145], v[222:225], v[106:109]
	v_mfma_f32_16x16x32_bf16 v[94:97], v[134:137], v[230:233], v[94:97]
	v_mfma_f32_16x16x32_bf16 v[90:93], v[142:145], v[230:233], v[90:93]
	v_mfma_f32_16x16x32_bf16 v[78:81], v[134:137], v[238:241], v[78:81]
	v_mfma_f32_16x16x32_bf16 v[74:77], v[142:145], v[238:241], v[74:77]
	s_setprio 0
	s_setprio 1
	v_mfma_f32_16x16x32_bf16 v[118:121], v[146:149], v[184:187], 0
	v_mfma_f32_16x16x32_bf16 v[114:117], v[154:157], v[184:187], 0
	v_mfma_f32_16x16x32_bf16 v[102:105], v[146:149], v[218:221], 0
	v_mfma_f32_16x16x32_bf16 v[98:101], v[154:157], v[218:221], 0
	v_mfma_f32_16x16x32_bf16 v[86:89], v[146:149], v[226:229], 0
	v_mfma_f32_16x16x32_bf16 v[82:85], v[154:157], v[226:229], 0
	v_mfma_f32_16x16x32_bf16 v[70:73], v[146:149], v[234:237], 0
	v_mfma_f32_16x16x32_bf16 v[66:69], v[154:157], v[234:237], 0
	v_mfma_f32_16x16x32_bf16 v[118:121], v[150:153], v[188:191], v[118:121]
	v_mfma_f32_16x16x32_bf16 v[114:117], v[158:161], v[188:191], v[114:117]
	v_mfma_f32_16x16x32_bf16 v[102:105], v[150:153], v[222:225], v[102:105]
	v_mfma_f32_16x16x32_bf16 v[98:101], v[158:161], v[222:225], v[98:101]
	v_mfma_f32_16x16x32_bf16 v[86:89], v[150:153], v[230:233], v[86:89]
	v_mfma_f32_16x16x32_bf16 v[82:85], v[158:161], v[230:233], v[82:85]
	v_mfma_f32_16x16x32_bf16 v[70:73], v[150:153], v[238:241], v[70:73]
	v_mfma_f32_16x16x32_bf16 v[66:69], v[158:161], v[238:241], v[66:69]
	s_setprio 0
	s_barrier
	s_add_i32 s56, s56, s36
	v_lshl_add_u64 v[242:243], s[24:25], 0, v[162:163]
	s_mov_b32 m0, s56
	ds_read_b128 v[184:187], v217 offset:16384
	ds_read_b128 v[188:191], v217 offset:17408
	ds_read_b128 v[218:221], v217 offset:18432
	ds_read_b128 v[222:225], v217 offset:19456
	ds_read_b128 v[226:229], v217 offset:20480
	ds_read_b128 v[230:233], v217 offset:21504
	ds_read_b128 v[234:237], v217 offset:22528
	ds_read_b128 v[238:241], v217 offset:23552
	global_load_lds_dwordx4 v[242:243], off
	s_add_i32 m0, s56, 0x2000
	s_add_u32 s56, s24, 0x4000
	v_lshl_add_u64 v[242:243], s[24:25], 0, v[178:179]
	s_addc_u32 s57, s25, 0
	s_add_i32 s58, s58, s36
	global_load_lds_dwordx4 v[242:243], off
	v_lshl_add_u64 v[242:243], s[56:57], 0, v[162:163]
	s_mov_b32 m0, s58
	s_nop 0
	global_load_lds_dwordx4 v[242:243], off
	v_lshl_add_u64 v[242:243], s[56:57], 0, v[178:179]
	s_add_i32 m0, s58, 0x2000
	s_nop 0
	global_load_lds_dwordx4 v[242:243], off
	v_lshl_add_u64 v[242:243], s[26:27], 0, v[174:175]
	s_mov_b32 m0, s37
	s_nop 0
	global_load_lds_dwordx4 v[242:243], off
	v_lshl_add_u64 v[242:243], s[26:27], 0, v[176:177]
	s_mov_b32 m0, s38
	s_nop 0
	global_load_lds_dwordx4 v[242:243], off
	s_waitcnt vmcnt(8)
	s_waitcnt lgkmcnt(0)
	s_barrier
; #define PG8_STAGE(bufoff, gbase, voff) do { _Pragma("unroll") for (int _i = 0; _i < 2; ++_i) \
;         __builtin_amdgcn_global_load_lds((const unsigned*)((const char*)(gbase) + (voff)[_i]), (PG8_LAS unsigned*)(lds + (bufoff) + ldsw + _i * 8192), 16, 0, 0); } while (0)
; #define PG8_LDA(dst, b, h) do { _Pragma("unroll") for (int m = 0; m < 4; ++m) _Pragma("unroll") for (int k = 0; k < 2; ++k) dst[m][k] = *(const PG8_LAS frag_t*)(lds + PG8_SA(b, h) + aoff + m * 2048 + k * 1024); } while (0)
; #define PG8_LDB(dst, b, h) do { _Pragma("unroll") for (int n = 0; n < 2; ++n) _Pragma("unroll") for (int k = 0; k < 2; ++k) dst[n][k] = *(const PG8_LAS frag_t*)(lds + PG8_SB(b, h) + boff + n * 2048 + k * 1024); } while (0)
; #define PG8_MMA(ai, bj, At, Bt) do { __builtin_amdgcn_s_setprio(1); _Pragma("unroll") for (int m = 0; m < 4; ++m) _Pragma("unroll") for (int n = 0; n < 2; ++n) _Pragma("unroll") for (int k = 0; k < 2; ++k) \
;         acc[ai][bj][m][n] = mma1v<MMAV>(Bt[n][k], At[m][k], acc[ai][bj][m][n]); __builtin_amdgcn_s_setprio(0); } while (0)
; #define PG8_WAIT_V(n) asm volatile("s_waitcnt vmcnt(" #n ")" ::: "memory")
; #define PG8_WAIT_L(n) asm volatile("s_waitcnt lgkmcnt(" #n ")" ::: "memory")
; #define PG8_BAR __builtin_amdgcn_s_barrier()
; #define PG8_SCHED __builtin_amdgcn_sched_barrier(0)
;     ...
;             PG8_WAIT_V(8); PG8_WAIT_L(0); PG8_BAR; PG8_MMA(1, 0, At, B0); PG8_MMA(1, 1, At, B1); PG8_BAR; PG8_SCHED;
;             PG8_LDB(B0, 1, 0); PG8_LDB(B1, 1, 1); PG8_SCHED; PG8_LDA(At, 1, 0); PG8_STAGE(PG8_SA(0, 1), a2 + hstep, voffA);
;             PG8_WAIT_V(8); PG8_WAIT_L(0); PG8_BAR; PG8_MMA(0, 0, At, B0); PG8_MMA(0, 1, At, B1); PG8_BAR; PG8_SCHED;
;             PG8_LDA(At, 1, 1); PG8_STAGE(PG8_SB(1, 0), b3, voffB); PG8_STAGE(PG8_SB(1, 1), b3 + hstepB, voffB); PG8_STAGE(PG8_SA(1, 0), a3, voffA);
;             PG8_WAIT_V(8); PG8_WAIT_L(0); PG8_BAR; PG8_MMA(1, 0, At, B0); PG8_MMA(1, 1, At, B1); PG8_BAR; PG8_SCHED;
	s_setprio 1
	s_waitcnt lgkmcnt(0)
	v_mfma_f32_16x16x32_bf16 v[62:65], v[130:133], v[184:187], 0
	v_mfma_f32_16x16x32_bf16 v[58:61], v[138:141], v[184:187], 0
	v_mfma_f32_16x16x32_bf16 v[46:49], v[130:133], v[218:221], 0
	v_mfma_f32_16x16x32_bf16 v[42:45], v[138:141], v[218:221], 0
	v_mfma_f32_16x16x32_bf16 v[30:33], v[130:133], v[226:229], 0
	v_mfma_f32_16x16x32_bf16 v[26:29], v[138:141], v[226:229], 0
	v_mfma_f32_16x16x32_bf16 v[14:17], v[130:133], v[234:237], 0
	v_mfma_f32_16x16x32_bf16 v[10:13], v[138:141], v[234:237], 0
	v_mfma_f32_16x16x32_bf16 v[62:65], v[134:137], v[188:191], v[62:65]
	v_mfma_f32_16x16x32_bf16 v[58:61], v[142:145], v[188:191], v[58:61]
	v_mfma_f32_16x16x32_bf16 v[46:49], v[134:137], v[222:225], v[46:49]
	v_mfma_f32_16x16x32_bf16 v[42:45], v[142:145], v[222:225], v[42:45]
	v_mfma_f32_16x16x32_bf16 v[30:33], v[134:137], v[230:233], v[30:33]
	v_mfma_f32_16x16x32_bf16 v[26:29], v[142:145], v[230:233], v[26:29]
	v_mfma_f32_16x16x32_bf16 v[14:17], v[134:137], v[238:241], v[14:17]
	v_mfma_f32_16x16x32_bf16 v[10:13], v[142:145], v[238:241], v[10:13]
	s_setprio 0
	s_setprio 1
	v_mfma_f32_16x16x32_bf16 v[54:57], v[146:149], v[184:187], 0
	v_mfma_f32_16x16x32_bf16 v[50:53], v[154:157], v[184:187], 0
	v_mfma_f32_16x16x32_bf16 v[38:41], v[146:149], v[218:221], 0
	v_mfma_f32_16x16x32_bf16 v[34:37], v[154:157], v[218:221], 0
	v_mfma_f32_16x16x32_bf16 v[22:25], v[146:149], v[226:229], 0
	v_mfma_f32_16x16x32_bf16 v[18:21], v[154:157], v[226:229], 0
	v_mfma_f32_16x16x32_bf16 v[6:9], v[146:149], v[234:237], 0
	v_mfma_f32_16x16x32_bf16 v[2:5], v[154:157], v[234:237], 0
	v_mfma_f32_16x16x32_bf16 v[54:57], v[150:153], v[188:191], v[54:57]
	v_mfma_f32_16x16x32_bf16 v[50:53], v[158:161], v[188:191], v[50:53]
	v_mfma_f32_16x16x32_bf16 v[38:41], v[150:153], v[222:225], v[38:41]
	v_mfma_f32_16x16x32_bf16 v[34:37], v[158:161], v[222:225], v[34:37]
	v_mfma_f32_16x16x32_bf16 v[22:25], v[150:153], v[230:233], v[22:25]
	v_mfma_f32_16x16x32_bf16 v[18:21], v[158:161], v[230:233], v[18:21]
	v_mfma_f32_16x16x32_bf16 v[6:9], v[150:153], v[238:241], v[6:9]
	v_mfma_f32_16x16x32_bf16 v[2:5], v[158:161], v[238:241], v[2:5]
	s_setprio 0
	s_barrier
	s_add_i32 s56, 0, 0x18000
	s_add_i32 s57, 0, 0x1c000
	v_add_u32_e32 v142, s56, v216
	v_add_u32_e32 v158, s57, v216
	ds_read_b128 v[130:133], v142
	ds_read_b128 v[134:137], v142 offset:1024
	ds_read_b128 v[138:141], v142 offset:2048
	ds_read_b128 v[142:145], v142 offset:3072
	ds_read_b128 v[146:149], v158
	ds_read_b128 v[150:153], v158 offset:1024
	ds_read_b128 v[154:157], v158 offset:2048
	ds_read_b128 v[158:161], v158 offset:3072
	s_add_u32 s26, s26, 0x4000
	s_addc_u32 s27, s27, 0
	s_mov_b32 m0, s39
	v_lshl_add_u64 v[242:243], s[26:27], 0, v[174:175]
	ds_read_b128 v[184:187], v217 offset:32768
	ds_read_b128 v[188:191], v217 offset:33792
	ds_read_b128 v[218:221], v217 offset:34816
	ds_read_b128 v[222:225], v217 offset:35840
	ds_read_b128 v[226:229], v217 offset:36864
	ds_read_b128 v[230:233], v217 offset:37888
	ds_read_b128 v[234:237], v217 offset:38912
	ds_read_b128 v[238:241], v217 offset:39936
	global_load_lds_dwordx4 v[242:243], off
	v_lshl_add_u64 v[242:243], s[26:27], 0, v[176:177]
	s_mov_b32 m0, s40
	s_nop 0
	global_load_lds_dwordx4 v[242:243], off
	s_waitcnt vmcnt(8)
	s_waitcnt lgkmcnt(0)
	s_barrier
	s_setprio 1
	s_waitcnt lgkmcnt(0)
	v_mfma_f32_16x16x32_bf16 v[126:129], v[130:133], v[184:187], v[126:129]
	v_mfma_f32_16x16x32_bf16 v[122:125], v[138:141], v[184:187], v[122:125]
	v_mfma_f32_16x16x32_bf16 v[110:113], v[130:133], v[218:221], v[110:113]
	v_mfma_f32_16x16x32_bf16 v[106:109], v[138:141], v[218:221], v[106:109]
	v_mfma_f32_16x16x32_bf16 v[94:97], v[130:133], v[226:229], v[94:97]
	v_mfma_f32_16x16x32_bf16 v[90:93], v[138:141], v[226:229], v[90:93]
	v_mfma_f32_16x16x32_bf16 v[78:81], v[130:133], v[234:237], v[78:81]
	v_mfma_f32_16x16x32_bf16 v[74:77], v[138:141], v[234:237], v[74:77]
	v_mfma_f32_16x16x32_bf16 v[126:129], v[134:137], v[188:191], v[126:129]
	v_mfma_f32_16x16x32_bf16 v[122:125], v[142:145], v[188:191], v[122:125]
	v_mfma_f32_16x16x32_bf16 v[110:113], v[134:137], v[222:225], v[110:113]
	v_mfma_f32_16x16x32_bf16 v[106:109], v[142:145], v[222:225], v[106:109]
	v_mfma_f32_16x16x32_bf16 v[94:97], v[134:137], v[230:233], v[94:97]
	v_mfma_f32_16x16x32_bf16 v[90:93], v[142:145], v[230:233], v[90:93]
	v_mfma_f32_16x16x32_bf16 v[78:81], v[134:137], v[238:241], v[78:81]
	v_mfma_f32_16x16x32_bf16 v[74:77], v[142:145], v[238:241], v[74:77]
	s_setprio 0
	s_setprio 1
	v_mfma_f32_16x16x32_bf16 v[118:121], v[146:149], v[184:187], v[118:121]
	v_mfma_f32_16x16x32_bf16 v[114:117], v[154:157], v[184:187], v[114:117]
	v_mfma_f32_16x16x32_bf16 v[102:105], v[146:149], v[218:221], v[102:105]
	v_mfma_f32_16x16x32_bf16 v[98:101], v[154:157], v[218:221], v[98:101]
	v_mfma_f32_16x16x32_bf16 v[86:89], v[146:149], v[226:229], v[86:89]
	v_mfma_f32_16x16x32_bf16 v[82:85], v[154:157], v[226:229], v[82:85]
	v_mfma_f32_16x16x32_bf16 v[70:73], v[146:149], v[234:237], v[70:73]
	v_mfma_f32_16x16x32_bf16 v[66:69], v[154:157], v[234:237], v[66:69]
	v_mfma_f32_16x16x32_bf16 v[118:121], v[150:153], v[188:191], v[118:121]
	v_mfma_f32_16x16x32_bf16 v[114:117], v[158:161], v[188:191], v[114:117]
	v_mfma_f32_16x16x32_bf16 v[102:105], v[150:153], v[222:225], v[102:105]
	v_mfma_f32_16x16x32_bf16 v[98:101], v[158:161], v[222:225], v[98:101]
	v_mfma_f32_16x16x32_bf16 v[86:89], v[150:153], v[230:233], v[86:89]
	v_mfma_f32_16x16x32_bf16 v[82:85], v[158:161], v[230:233], v[82:85]
	v_mfma_f32_16x16x32_bf16 v[70:73], v[150:153], v[238:241], v[70:73]
	v_mfma_f32_16x16x32_bf16 v[66:69], v[158:161], v[238:241], v[66:69]
	s_setprio 0
	s_barrier
; #define PG8_STAGE(bufoff, gbase, voff) do { _Pragma("unroll") for (int _i = 0; _i < 2; ++_i) \
;         __builtin_amdgcn_global_load_lds((const unsigned*)((const char*)(gbase) + (voff)[_i]), (PG8_LAS unsigned*)(lds + (bufoff) + ldsw + _i * 8192), 16, 0, 0); } while (0)
; #define PG8_LDA(dst, b, h) do { _Pragma("unroll") for (int m = 0; m < 4; ++m) _Pragma("unroll") for (int k = 0; k < 2; ++k) dst[m][k] = *(const PG8_LAS frag_t*)(lds + PG8_SA(b, h) + aoff + m * 2048 + k * 1024); } while (0)
; #define PG8_MMA(ai, bj, At, Bt) do { __builtin_amdgcn_s_setprio(1); _Pragma("unroll") for (int m = 0; m < 4; ++m) _Pragma("unroll") for (int n = 0; n < 2; ++n) _Pragma("unroll") for (int k = 0; k < 2; ++k) \
;         acc[ai][bj][m][n] = mma1v<MMAV>(Bt[n][k], At[m][k], acc[ai][bj][m][n]); __builtin_amdgcn_s_setprio(0); } while (0)
; #define PG8_WAIT_V(n) asm volatile("s_waitcnt vmcnt(" #n ")" ::: "memory")
; #define PG8_WAIT_L(n) asm volatile("s_waitcnt lgkmcnt(" #n ")" ::: "memory")
; #define PG8_BAR __builtin_amdgcn_s_barrier()
; #define PG8_SCHED __builtin_amdgcn_sched_barrier(0)
;     ...
;             PG8_WAIT_V(8); PG8_WAIT_L(0); PG8_BAR; PG8_MMA(0, 0, At, B0); PG8_MMA(0, 1, At, B1); PG8_BAR; PG8_SCHED;
;             PG8_LDA(At, 1, 1); PG8_STAGE(PG8_SB(1, 0), b3, voffB); PG8_STAGE(PG8_SB(1, 1), b3 + hstepB, voffB); PG8_STAGE(PG8_SA(1, 0), a3, voffA);
;             PG8_WAIT_V(8); PG8_WAIT_L(0); PG8_BAR; PG8_MMA(1, 0, At, B0); PG8_MMA(1, 1, At, B1); PG8_BAR; PG8_SCHED;
	s_add_u32 s26, s24, 0x8000
	s_addc_u32 s27, s25, 0
	s_add_i32 s56, s56, s36
	v_lshl_add_u64 v[242:243], s[26:27], 0, v[162:163]
	s_mov_b32 m0, s56
	ds_read_b128 v[184:187], v217 offset:49152
	ds_read_b128 v[188:191], v217 offset:50176
	ds_read_b128 v[218:221], v217 offset:51200
	ds_read_b128 v[222:225], v217 offset:52224
	ds_read_b128 v[226:229], v217 offset:53248
	ds_read_b128 v[230:233], v217 offset:54272
	ds_read_b128 v[234:237], v217 offset:55296
	ds_read_b128 v[238:241], v217 offset:56320
	global_load_lds_dwordx4 v[242:243], off
	s_add_i32 m0, s56, 0x2000
	s_add_u32 s24, s24, 0xc000
	v_lshl_add_u64 v[242:243], s[26:27], 0, v[178:179]
	s_addc_u32 s25, s25, 0
	s_add_i32 s26, s57, s36
	global_load_lds_dwordx4 v[242:243], off
	v_lshl_add_u64 v[242:243], s[24:25], 0, v[162:163]
	s_mov_b32 m0, s26
	s_nop 0
	global_load_lds_dwordx4 v[242:243], off
	v_lshl_add_u64 v[242:243], s[24:25], 0, v[178:179]
	s_add_i32 m0, s26, 0x2000
	s_nop 0
	global_load_lds_dwordx4 v[242:243], off
	v_lshl_add_u64 v[242:243], s[8:9], 0, v[174:175]
	s_mov_b32 m0, s44
	s_nop 0
	global_load_lds_dwordx4 v[242:243], off
	v_lshl_add_u64 v[242:243], s[8:9], 0, v[176:177]
	s_mov_b32 m0, s45
	s_nop 0
	global_load_lds_dwordx4 v[242:243], off
	s_waitcnt vmcnt(8)
	s_waitcnt lgkmcnt(0)
	s_barrier
	s_setprio 1
	s_waitcnt lgkmcnt(0)
	v_mfma_f32_16x16x32_bf16 v[62:65], v[130:133], v[184:187], v[62:65]
	v_mfma_f32_16x16x32_bf16 v[58:61], v[138:141], v[184:187], v[58:61]
	v_mfma_f32_16x16x32_bf16 v[46:49], v[130:133], v[218:221], v[46:49]
	v_mfma_f32_16x16x32_bf16 v[42:45], v[138:141], v[218:221], v[42:45]
	v_mfma_f32_16x16x32_bf16 v[30:33], v[130:133], v[226:229], v[30:33]
	v_mfma_f32_16x16x32_bf16 v[26:29], v[138:141], v[226:229], v[26:29]
	v_mfma_f32_16x16x32_bf16 v[14:17], v[130:133], v[234:237], v[14:17]
	v_mfma_f32_16x16x32_bf16 v[10:13], v[138:141], v[234:237], v[10:13]
	v_mfma_f32_16x16x32_bf16 v[62:65], v[134:137], v[188:191], v[62:65]
	v_mfma_f32_16x16x32_bf16 v[58:61], v[142:145], v[188:191], v[58:61]
	v_mfma_f32_16x16x32_bf16 v[46:49], v[134:137], v[222:225], v[46:49]
	v_mfma_f32_16x16x32_bf16 v[42:45], v[142:145], v[222:225], v[42:45]
	v_mfma_f32_16x16x32_bf16 v[30:33], v[134:137], v[230:233], v[30:33]
	v_mfma_f32_16x16x32_bf16 v[26:29], v[142:145], v[230:233], v[26:29]
	v_mfma_f32_16x16x32_bf16 v[14:17], v[134:137], v[238:241], v[14:17]
	v_mfma_f32_16x16x32_bf16 v[10:13], v[142:145], v[238:241], v[10:13]
	s_setprio 0
	s_setprio 1
	v_mfma_f32_16x16x32_bf16 v[54:57], v[146:149], v[184:187], v[54:57]
	v_mfma_f32_16x16x32_bf16 v[50:53], v[154:157], v[184:187], v[50:53]
	v_mfma_f32_16x16x32_bf16 v[38:41], v[146:149], v[218:221], v[38:41]
	v_mfma_f32_16x16x32_bf16 v[34:37], v[154:157], v[218:221], v[34:37]
	v_mfma_f32_16x16x32_bf16 v[22:25], v[146:149], v[226:229], v[22:25]
	v_mfma_f32_16x16x32_bf16 v[18:21], v[154:157], v[226:229], v[18:21]
	v_mfma_f32_16x16x32_bf16 v[6:9], v[146:149], v[234:237], v[6:9]
	v_mfma_f32_16x16x32_bf16 v[2:5], v[154:157], v[234:237], v[2:5]
	v_mfma_f32_16x16x32_bf16 v[54:57], v[150:153], v[188:191], v[54:57]
	v_mfma_f32_16x16x32_bf16 v[50:53], v[158:161], v[188:191], v[50:53]
	v_mfma_f32_16x16x32_bf16 v[38:41], v[150:153], v[222:225], v[38:41]
	v_mfma_f32_16x16x32_bf16 v[34:37], v[158:161], v[222:225], v[34:37]
	v_mfma_f32_16x16x32_bf16 v[22:25], v[150:153], v[230:233], v[22:25]
	v_mfma_f32_16x16x32_bf16 v[18:21], v[158:161], v[230:233], v[18:21]
	v_mfma_f32_16x16x32_bf16 v[6:9], v[150:153], v[238:241], v[6:9]
	v_mfma_f32_16x16x32_bf16 v[2:5], v[158:161], v[238:241], v[2:5]
	s_setprio 0
	s_barrier
	s_add_i32 s55, s55, 2
	s_add_u32 s6, s6, 0x10000
	s_addc_u32 s7, s7, 0
	s_add_u32 s53, s53, 0x10000
	s_addc_u32 s54, s54, 0

; #define PG8_STAGE(bufoff, gbase, voff) do { _Pragma("unroll") for (int _i = 0; _i < 2; ++_i) \
;         __builtin_amdgcn_global_load_lds((const unsigned*)((const char*)(gbase) + (voff)[_i]), (PG8_LAS unsigned*)(lds + (bufoff) + ldsw + _i * 8192), 16, 0, 0); } while (0)
; #define PG8_LDA(dst, b, h) do { _Pragma("unroll") for (int m = 0; m < 4; ++m) _Pragma("unroll") for (int k = 0; k < 2; ++k) dst[m][k] = *(const PG8_LAS frag_t*)(lds + PG8_SA(b, h) + aoff + m * 2048 + k * 1024); } while (0)
; #define PG8_LDB(dst, b, h) do { _Pragma("unroll") for (int n = 0; n < 2; ++n) _Pragma("unroll") for (int k = 0; k < 2; ++k) dst[n][k] = *(const PG8_LAS frag_t*)(lds + PG8_SB(b, h) + boff + n * 2048 + k * 1024); } while (0)
; #define PG8_MMA(ai, bj, At, Bt) do { __builtin_amdgcn_s_setprio(1); _Pragma("unroll") for (int m = 0; m < 4; ++m) _Pragma("unroll") for (int n = 0; n < 2; ++n) _Pragma("unroll") for (int k = 0; k < 2; ++k) \
;         acc[ai][bj][m][n] = mma1v<MMAV>(Bt[n][k], At[m][k], acc[ai][bj][m][n]); __builtin_amdgcn_s_setprio(0); } while (0)
; #define PG8_WAIT_V(n) asm volatile("s_waitcnt vmcnt(" #n ")" ::: "memory")
; #define PG8_WAIT_L(n) asm volatile("s_waitcnt lgkmcnt(" #n ")" ::: "memory")
;     ...
;         const bool has_next = S.next(ui + 1, nxt);
;         const char* nA = has_next ? (const char*)g.A + (size_t)nxt.pm * tstep : cA; const char* nB = has_next ? (const char*)g.Bt + (size_t)nxt.pn * tstep : cB;
;         for (int t = 0; t < nt; t += 2) {
;             const bool last = (t == nt - 2);
;             const char* a1 = cA + (size_t)(t + 1) * kstep;
;             const char* a2 = last ? nA : cA + (size_t)(t + 2) * kstep; const char* b2 = last ? nB : cB + (size_t)(t + 2) * kstepB;
;             const char* a3 = a2 + kstep; const char* b3 = b2 + kstepB;
;             if (last && has_next) S.a_ready(nxt);
;             if constexpr (SP2) {
;             PG8_LDB(B0, 0, 0); PG8_LDB(B1, 0, 1); PG8_SCHED; PG8_LDA(At, 0, 0); PG8_STAGE(PG8_SA(1, 1), a1 + hstep, voffA);
;             PG8_WAIT_V(8); PG8_WAIT_L(0); PG8_BAR; PG8_MMA(0, 0, At, B0); PG8_MMA(0, 1, At, B1); PG8_BAR; PG8_SCHED;
;             PG8_LDA(At, 0, 1); PG8_STAGE(PG8_SB(0, 0), b2, voffB); PG8_STAGE(PG8_SB(0, 1), b2 + hstepB, voffB); PG8_STAGE(PG8_SA(0, 0), a2, voffA);
;             PG8_WAIT_V(8); PG8_WAIT_L(0); PG8_BAR; PG8_MMA(1, 0, At, B0); PG8_MMA(1, 1, At, B1); PG8_BAR; PG8_SCHED;
.LBB0_368:
	s_ashr_i32 s31, s30, 31
	s_lshl_b64 s[10:11], s[30:31], 20
	s_add_u32 s34, s48, s10
	s_addc_u32 s35, s49, s11
	s_and_b64 s[10:11], s[6:7], exec
	s_cselect_b32 s31, s35, s9
	s_cselect_b32 s39, s34, s8
	s_ashr_i32 s29, s28, 31
	s_lshl_b64 s[10:11], s[28:29], 20
	s_add_u32 s36, s50, s10
	s_addc_u32 s37, s51, s11
	s_and_b64 s[10:11], s[6:7], exec
	s_cselect_b32 s29, s37, s1
	s_cselect_b32 s40, s36, s0
	s_add_u32 s41, s0, 0x10000
	s_addc_u32 s42, s1, 0
	s_add_u32 s0, s8, 0x80080
	s_addc_u32 s1, s9, 0
	s_mov_b32 s43, -2
	s_add_u32 s8, s0, 0xfff80080
	s_addc_u32 s9, s1, -1
	s_add_i32 s80, 0, 0x10000
	s_cmp_eq_u32 s43, 28
	s_cselect_b32 s11, s31, s9
	s_cselect_b32 s10, s39, s8
	s_cselect_b32 s9, s29, s42
	s_cselect_b32 s8, s40, s41
	s_add_i32 s82, 0, 0x14000
	v_add_u32_e32 v154, s80, v161
	v_add_u32_e32 v158, s82, v161
	ds_read_b128 v[130:133], v154
	ds_read_b128 v[134:137], v154 offset:1024
	ds_read_b128 v[138:141], v154 offset:2048
	ds_read_b128 v[154:157], v154 offset:3072
	ds_read_b128 v[176:179], v158
	ds_read_b128 v[180:183], v158 offset:1024
	ds_read_b128 v[184:187], v158 offset:2048
	ds_read_b128 v[188:191], v158 offset:3072
	v_lshl_add_u64 v[248:249], s[0:1], 0, v[150:151]
	s_add_i32 m0, s21, 0xc000
	ds_read_b128 v[216:219], v175
	ds_read_b128 v[220:223], v175 offset:1024
	ds_read_b128 v[224:227], v175 offset:2048
	ds_read_b128 v[228:231], v175 offset:3072
	ds_read_b128 v[232:235], v175 offset:4096
	ds_read_b128 v[236:239], v175 offset:5120
	ds_read_b128 v[240:243], v175 offset:6144
	ds_read_b128 v[244:247], v175 offset:7168
	global_load_lds_dwordx4 v[248:249], off
	v_lshl_add_u64 v[248:249], s[0:1], 0, v[152:153]
	s_add_i32 m0, s21, 0xe000
	s_nop 0
	global_load_lds_dwordx4 v[248:249], off
	s_waitcnt vmcnt(24)
	s_waitcnt lgkmcnt(0)
	s_barrier
	s_setprio 1
	s_waitcnt lgkmcnt(0)
	v_mfma_f32_16x16x32_bf16 v[126:129], v[130:133], v[216:219], 0
	v_mfma_f32_16x16x32_bf16 v[122:125], v[138:141], v[216:219], 0
	v_mfma_f32_16x16x32_bf16 v[110:113], v[130:133], v[224:227], 0
	v_mfma_f32_16x16x32_bf16 v[106:109], v[138:141], v[224:227], 0
	v_mfma_f32_16x16x32_bf16 v[94:97], v[130:133], v[232:235], 0
	v_mfma_f32_16x16x32_bf16 v[90:93], v[138:141], v[232:235], 0
	v_mfma_f32_16x16x32_bf16 v[78:81], v[130:133], v[240:243], 0
	v_mfma_f32_16x16x32_bf16 v[74:77], v[138:141], v[240:243], 0
	v_mfma_f32_16x16x32_bf16 v[126:129], v[134:137], v[220:223], v[126:129]
	v_mfma_f32_16x16x32_bf16 v[122:125], v[154:157], v[220:223], v[122:125]
	v_mfma_f32_16x16x32_bf16 v[110:113], v[134:137], v[228:231], v[110:113]
	v_mfma_f32_16x16x32_bf16 v[106:109], v[154:157], v[228:231], v[106:109]
	v_mfma_f32_16x16x32_bf16 v[94:97], v[134:137], v[236:239], v[94:97]
	v_mfma_f32_16x16x32_bf16 v[90:93], v[154:157], v[236:239], v[90:93]
	v_mfma_f32_16x16x32_bf16 v[78:81], v[134:137], v[244:247], v[78:81]
	v_mfma_f32_16x16x32_bf16 v[74:77], v[154:157], v[244:247], v[74:77]
	s_setprio 0
	s_setprio 1
	v_mfma_f32_16x16x32_bf16 v[118:121], v[176:179], v[216:219], 0
	v_mfma_f32_16x16x32_bf16 v[114:117], v[184:187], v[216:219], 0
	v_mfma_f32_16x16x32_bf16 v[102:105], v[176:179], v[224:227], 0
	v_mfma_f32_16x16x32_bf16 v[98:101], v[184:187], v[224:227], 0
	v_mfma_f32_16x16x32_bf16 v[86:89], v[176:179], v[232:235], 0
	v_mfma_f32_16x16x32_bf16 v[82:85], v[184:187], v[232:235], 0
	v_mfma_f32_16x16x32_bf16 v[70:73], v[176:179], v[240:243], 0
	v_mfma_f32_16x16x32_bf16 v[66:69], v[184:187], v[240:243], 0
	v_mfma_f32_16x16x32_bf16 v[118:121], v[180:183], v[220:223], v[118:121]
	v_mfma_f32_16x16x32_bf16 v[114:117], v[188:191], v[220:223], v[114:117]
	v_mfma_f32_16x16x32_bf16 v[102:105], v[180:183], v[228:231], v[102:105]
	v_mfma_f32_16x16x32_bf16 v[98:101], v[188:191], v[228:231], v[98:101]
	v_mfma_f32_16x16x32_bf16 v[86:89], v[180:183], v[236:239], v[86:89]
	v_mfma_f32_16x16x32_bf16 v[82:85], v[188:191], v[236:239], v[82:85]
	v_mfma_f32_16x16x32_bf16 v[70:73], v[180:183], v[244:247], v[70:73]
	v_mfma_f32_16x16x32_bf16 v[66:69], v[188:191], v[244:247], v[66:69]
	s_setprio 0
	s_barrier
	s_add_i32 s80, s80, s53
	v_lshl_add_u64 v[248:249], s[8:9], 0, v[142:143]
	s_mov_b32 m0, s80
	ds_read_b128 v[216:219], v175 offset:16384
	ds_read_b128 v[220:223], v175 offset:17408
	ds_read_b128 v[224:227], v175 offset:18432
	ds_read_b128 v[228:231], v175 offset:19456
	ds_read_b128 v[232:235], v175 offset:20480
	ds_read_b128 v[236:239], v175 offset:21504
	ds_read_b128 v[240:243], v175 offset:22528
	ds_read_b128 v[244:247], v175 offset:23552
	global_load_lds_dwordx4 v[248:249], off
	s_add_i32 m0, s80, 0x2000
	s_add_u32 s80, s8, 0x4000
	v_lshl_add_u64 v[248:249], s[8:9], 0, v[146:147]
	s_addc_u32 s81, s9, 0
	s_add_i32 s82, s82, s53
	global_load_lds_dwordx4 v[248:249], off
	v_lshl_add_u64 v[248:249], s[80:81], 0, v[142:143]
	s_mov_b32 m0, s82
	v_lshl_add_u64 v[250:251], s[10:11], 0, v[144:145]
	global_load_lds_dwordx4 v[248:249], off
	v_lshl_add_u64 v[248:249], s[80:81], 0, v[146:147]
	s_add_i32 m0, s82, 0x2000
	s_nop 0
	global_load_lds_dwordx4 v[248:249], off
	v_lshl_add_u64 v[248:249], s[10:11], 0, v[162:163]
	s_mov_b32 m0, s21
	s_nop 0
	global_load_lds_dwordx4 v[248:249], off
	s_mov_b32 m0, s54
	s_nop 0
	global_load_lds_dwordx4 v[250:251], off
	s_waitcnt vmcnt(8)
	s_waitcnt lgkmcnt(0)
	s_barrier
; #define PG8_STAGE(bufoff, gbase, voff) do { _Pragma("unroll") for (int _i = 0; _i < 2; ++_i) \
;         __builtin_amdgcn_global_load_lds((const unsigned*)((const char*)(gbase) + (voff)[_i]), (PG8_LAS unsigned*)(lds + (bufoff) + ldsw + _i * 8192), 16, 0, 0); } while (0)
; #define PG8_LDA(dst, b, h) do { _Pragma("unroll") for (int m = 0; m < 4; ++m) _Pragma("unroll") for (int k = 0; k < 2; ++k) dst[m][k] = *(const PG8_LAS frag_t*)(lds + PG8_SA(b, h) + aoff + m * 2048 + k * 1024); } while (0)
; #define PG8_LDB(dst, b, h) do { _Pragma("unroll") for (int n = 0; n < 2; ++n) _Pragma("unroll") for (int k = 0; k < 2; ++k) dst[n][k] = *(const PG8_LAS frag_t*)(lds + PG8_SB(b, h) + boff + n * 2048 + k * 1024); } while (0)
; #define PG8_MMA(ai, bj, At, Bt) do { __builtin_amdgcn_s_setprio(1); _Pragma("unroll") for (int m = 0; m < 4; ++m) _Pragma("unroll") for (int n = 0; n < 2; ++n) _Pragma("unroll") for (int k = 0; k < 2; ++k) \
;         acc[ai][bj][m][n] = mma1v<MMAV>(Bt[n][k], At[m][k], acc[ai][bj][m][n]); __builtin_amdgcn_s_setprio(0); } while (0)
; #define PG8_WAIT_V(n) asm volatile("s_waitcnt vmcnt(" #n ")" ::: "memory")
; #define PG8_WAIT_L(n) asm volatile("s_waitcnt lgkmcnt(" #n ")" ::: "memory")
; #define PG8_BAR __builtin_amdgcn_s_barrier()
; #define PG8_SCHED __builtin_amdgcn_sched_barrier(0)
;     ...
;             PG8_WAIT_V(8); PG8_WAIT_L(0); PG8_BAR; PG8_MMA(1, 0, At, B0); PG8_MMA(1, 1, At, B1); PG8_BAR; PG8_SCHED;
;             PG8_LDB(B0, 1, 0); PG8_LDB(B1, 1, 1); PG8_SCHED; PG8_LDA(At, 1, 0); PG8_STAGE(PG8_SA(0, 1), a2 + hstep, voffA);
;             PG8_WAIT_V(8); PG8_WAIT_L(0); PG8_BAR; PG8_MMA(0, 0, At, B0); PG8_MMA(0, 1, At, B1); PG8_BAR; PG8_SCHED;
;             PG8_LDA(At, 1, 1); PG8_STAGE(PG8_SB(1, 0), b3, voffB); PG8_STAGE(PG8_SB(1, 1), b3 + hstepB, voffB); PG8_STAGE(PG8_SA(1, 0), a3, voffA);
;             PG8_WAIT_V(8); PG8_WAIT_L(0); PG8_BAR; PG8_MMA(1, 0, At, B0); PG8_MMA(1, 1, At, B1); PG8_BAR; PG8_SCHED;
	s_setprio 1
	s_waitcnt lgkmcnt(0)
	v_mfma_f32_16x16x32_bf16 v[62:65], v[130:133], v[216:219], 0
	v_mfma_f32_16x16x32_bf16 v[58:61], v[138:141], v[216:219], 0
	v_mfma_f32_16x16x32_bf16 v[46:49], v[130:133], v[224:227], 0
	v_mfma_f32_16x16x32_bf16 v[42:45], v[138:141], v[224:227], 0
	v_mfma_f32_16x16x32_bf16 v[30:33], v[130:133], v[232:235], 0
	v_mfma_f32_16x16x32_bf16 v[26:29], v[138:141], v[232:235], 0
	v_mfma_f32_16x16x32_bf16 v[14:17], v[130:133], v[240:243], 0
	v_mfma_f32_16x16x32_bf16 v[10:13], v[138:141], v[240:243], 0
	v_mfma_f32_16x16x32_bf16 v[62:65], v[134:137], v[220:223], v[62:65]
	v_mfma_f32_16x16x32_bf16 v[58:61], v[154:157], v[220:223], v[58:61]
	v_mfma_f32_16x16x32_bf16 v[46:49], v[134:137], v[228:231], v[46:49]
	v_mfma_f32_16x16x32_bf16 v[42:45], v[154:157], v[228:231], v[42:45]
	v_mfma_f32_16x16x32_bf16 v[30:33], v[134:137], v[236:239], v[30:33]
	v_mfma_f32_16x16x32_bf16 v[26:29], v[154:157], v[236:239], v[26:29]
	v_mfma_f32_16x16x32_bf16 v[14:17], v[134:137], v[244:247], v[14:17]
	v_mfma_f32_16x16x32_bf16 v[10:13], v[154:157], v[244:247], v[10:13]
	s_setprio 0
	s_setprio 1
	v_mfma_f32_16x16x32_bf16 v[54:57], v[176:179], v[216:219], 0
	v_mfma_f32_16x16x32_bf16 v[50:53], v[184:187], v[216:219], 0
	v_mfma_f32_16x16x32_bf16 v[38:41], v[176:179], v[224:227], 0
	v_mfma_f32_16x16x32_bf16 v[34:37], v[184:187], v[224:227], 0
	v_mfma_f32_16x16x32_bf16 v[22:25], v[176:179], v[232:235], 0
	v_mfma_f32_16x16x32_bf16 v[18:21], v[184:187], v[232:235], 0
	v_mfma_f32_16x16x32_bf16 v[6:9], v[176:179], v[240:243], 0
	v_mfma_f32_16x16x32_bf16 v[2:5], v[184:187], v[240:243], 0
	v_mfma_f32_16x16x32_bf16 v[54:57], v[180:183], v[220:223], v[54:57]
	v_mfma_f32_16x16x32_bf16 v[50:53], v[188:191], v[220:223], v[50:53]
	v_mfma_f32_16x16x32_bf16 v[38:41], v[180:183], v[228:231], v[38:41]
	v_mfma_f32_16x16x32_bf16 v[34:37], v[188:191], v[228:231], v[34:37]
	v_mfma_f32_16x16x32_bf16 v[22:25], v[180:183], v[236:239], v[22:25]
	v_mfma_f32_16x16x32_bf16 v[18:21], v[188:191], v[236:239], v[18:21]
	v_mfma_f32_16x16x32_bf16 v[6:9], v[180:183], v[244:247], v[6:9]
	v_mfma_f32_16x16x32_bf16 v[2:5], v[188:191], v[244:247], v[2:5]
	s_setprio 0
	s_barrier
	s_add_i32 s80, 0, 0x18000
	s_add_i32 s81, 0, 0x1c000
	v_add_u32_e32 v154, s80, v161
	v_add_u32_e32 v158, s81, v161
	ds_read_b128 v[130:133], v154
	ds_read_b128 v[134:137], v154 offset:1024
	ds_read_b128 v[138:141], v154 offset:2048
	ds_read_b128 v[154:157], v154 offset:3072
	ds_read_b128 v[176:179], v158
	ds_read_b128 v[180:183], v158 offset:1024
	ds_read_b128 v[184:187], v158 offset:2048
	ds_read_b128 v[188:191], v158 offset:3072
	s_add_u32 s10, s10, 0x80000
	s_addc_u32 s11, s11, 0
	s_mov_b32 m0, s55
	v_lshl_add_u64 v[252:253], s[10:11], 0, v[162:163]
	ds_read_b128 v[216:219], v175 offset:32768
	ds_read_b128 v[220:223], v175 offset:33792
	ds_read_b128 v[224:227], v175 offset:34816
	ds_read_b128 v[228:231], v175 offset:35840
	ds_read_b128 v[232:235], v175 offset:36864
	ds_read_b128 v[236:239], v175 offset:37888
	ds_read_b128 v[240:243], v175 offset:38912
	ds_read_b128 v[244:247], v175 offset:39936
	global_load_lds_dwordx4 v[252:253], off
	v_lshl_add_u64 v[252:253], s[10:11], 0, v[144:145]
	s_mov_b32 m0, s56
	s_nop 0
	global_load_lds_dwordx4 v[252:253], off
	s_waitcnt vmcnt(8)
	s_waitcnt lgkmcnt(0)
	s_barrier
	s_setprio 1
	s_waitcnt lgkmcnt(0)
	v_mfma_f32_16x16x32_bf16 v[126:129], v[130:133], v[216:219], v[126:129]
	v_mfma_f32_16x16x32_bf16 v[122:125], v[138:141], v[216:219], v[122:125]
	v_mfma_f32_16x16x32_bf16 v[110:113], v[130:133], v[224:227], v[110:113]
	v_mfma_f32_16x16x32_bf16 v[106:109], v[138:141], v[224:227], v[106:109]
	v_mfma_f32_16x16x32_bf16 v[94:97], v[130:133], v[232:235], v[94:97]
	v_mfma_f32_16x16x32_bf16 v[90:93], v[138:141], v[232:235], v[90:93]
	v_mfma_f32_16x16x32_bf16 v[78:81], v[130:133], v[240:243], v[78:81]
	v_mfma_f32_16x16x32_bf16 v[74:77], v[138:141], v[240:243], v[74:77]
	v_mfma_f32_16x16x32_bf16 v[126:129], v[134:137], v[220:223], v[126:129]
	v_mfma_f32_16x16x32_bf16 v[122:125], v[154:157], v[220:223], v[122:125]
	v_mfma_f32_16x16x32_bf16 v[110:113], v[134:137], v[228:231], v[110:113]
	v_mfma_f32_16x16x32_bf16 v[106:109], v[154:157], v[228:231], v[106:109]
	v_mfma_f32_16x16x32_bf16 v[94:97], v[134:137], v[236:239], v[94:97]
	v_mfma_f32_16x16x32_bf16 v[90:93], v[154:157], v[236:239], v[90:93]
	v_mfma_f32_16x16x32_bf16 v[78:81], v[134:137], v[244:247], v[78:81]
	v_mfma_f32_16x16x32_bf16 v[74:77], v[154:157], v[244:247], v[74:77]
	s_setprio 0
	s_setprio 1
	v_mfma_f32_16x16x32_bf16 v[118:121], v[176:179], v[216:219], v[118:121]
	v_mfma_f32_16x16x32_bf16 v[114:117], v[184:187], v[216:219], v[114:117]
	v_mfma_f32_16x16x32_bf16 v[102:105], v[176:179], v[224:227], v[102:105]
	v_mfma_f32_16x16x32_bf16 v[98:101], v[184:187], v[224:227], v[98:101]
	v_mfma_f32_16x16x32_bf16 v[86:89], v[176:179], v[232:235], v[86:89]
	v_mfma_f32_16x16x32_bf16 v[82:85], v[184:187], v[232:235], v[82:85]
	v_mfma_f32_16x16x32_bf16 v[70:73], v[176:179], v[240:243], v[70:73]
	v_mfma_f32_16x16x32_bf16 v[66:69], v[184:187], v[240:243], v[66:69]
	v_mfma_f32_16x16x32_bf16 v[118:121], v[180:183], v[220:223], v[118:121]
	v_mfma_f32_16x16x32_bf16 v[114:117], v[188:191], v[220:223], v[114:117]
	v_mfma_f32_16x16x32_bf16 v[102:105], v[180:183], v[228:231], v[102:105]
	v_mfma_f32_16x16x32_bf16 v[98:101], v[188:191], v[228:231], v[98:101]
	v_mfma_f32_16x16x32_bf16 v[86:89], v[180:183], v[236:239], v[86:89]
	v_mfma_f32_16x16x32_bf16 v[82:85], v[188:191], v[236:239], v[82:85]
	v_mfma_f32_16x16x32_bf16 v[70:73], v[180:183], v[244:247], v[70:73]
	v_mfma_f32_16x16x32_bf16 v[66:69], v[188:191], v[244:247], v[66:69]
	s_setprio 0
	s_barrier
; #define PG8_STAGE(bufoff, gbase, voff) do { _Pragma("unroll") for (int _i = 0; _i < 2; ++_i) \
;         __builtin_amdgcn_global_load_lds((const unsigned*)((const char*)(gbase) + (voff)[_i]), (PG8_LAS unsigned*)(lds + (bufoff) + ldsw + _i * 8192), 16, 0, 0); } while (0)
; #define PG8_LDA(dst, b, h) do { _Pragma("unroll") for (int m = 0; m < 4; ++m) _Pragma("unroll") for (int k = 0; k < 2; ++k) dst[m][k] = *(const PG8_LAS frag_t*)(lds + PG8_SA(b, h) + aoff + m * 2048 + k * 1024); } while (0)
; #define PG8_MMA(ai, bj, At, Bt) do { __builtin_amdgcn_s_setprio(1); _Pragma("unroll") for (int m = 0; m < 4; ++m) _Pragma("unroll") for (int n = 0; n < 2; ++n) _Pragma("unroll") for (int k = 0; k < 2; ++k) \
;         acc[ai][bj][m][n] = mma1v<MMAV>(Bt[n][k], At[m][k], acc[ai][bj][m][n]); __builtin_amdgcn_s_setprio(0); } while (0)
; #define PG8_WAIT_V(n) asm volatile("s_waitcnt vmcnt(" #n ")" ::: "memory")
; #define PG8_WAIT_L(n) asm volatile("s_waitcnt lgkmcnt(" #n ")" ::: "memory")
; #define PG8_BAR __builtin_amdgcn_s_barrier()
; #define PG8_SCHED __builtin_amdgcn_sched_barrier(0)
;     ...
;             PG8_WAIT_V(8); PG8_WAIT_L(0); PG8_BAR; PG8_MMA(0, 0, At, B0); PG8_MMA(0, 1, At, B1); PG8_BAR; PG8_SCHED;
;             PG8_LDA(At, 1, 1); PG8_STAGE(PG8_SB(1, 0), b3, voffB); PG8_STAGE(PG8_SB(1, 1), b3 + hstepB, voffB); PG8_STAGE(PG8_SA(1, 0), a3, voffA);
;             PG8_WAIT_V(8); PG8_WAIT_L(0); PG8_BAR; PG8_MMA(1, 0, At, B0); PG8_MMA(1, 1, At, B1); PG8_BAR; PG8_SCHED;
	s_add_u32 s10, s8, 0x8000
	s_addc_u32 s11, s9, 0
	s_add_i32 s80, s80, s53
	v_lshl_add_u64 v[252:253], s[10:11], 0, v[142:143]
	s_mov_b32 m0, s80
	ds_read_b128 v[216:219], v175 offset:49152
	ds_read_b128 v[220:223], v175 offset:50176
	ds_read_b128 v[224:227], v175 offset:51200
	ds_read_b128 v[228:231], v175 offset:52224
	ds_read_b128 v[232:235], v175 offset:53248
	ds_read_b128 v[236:239], v175 offset:54272
	ds_read_b128 v[240:243], v175 offset:55296
	ds_read_b128 v[244:247], v175 offset:56320
	global_load_lds_dwordx4 v[252:253], off
	s_add_i32 m0, s80, 0x2000
	s_add_u32 s8, s8, 0xc000
	v_lshl_add_u64 v[252:253], s[10:11], 0, v[146:147]
	s_addc_u32 s9, s9, 0
	s_add_i32 s10, s81, s53
	global_load_lds_dwordx4 v[252:253], off
	v_lshl_add_u64 v[252:253], s[8:9], 0, v[142:143]
	s_mov_b32 m0, s10
	v_lshl_add_u64 v[248:249], v[248:249], 0, s[78:79]
	global_load_lds_dwordx4 v[252:253], off
	v_lshl_add_u64 v[252:253], s[8:9], 0, v[146:147]
	s_add_i32 m0, s10, 0x2000
	s_nop 0
	global_load_lds_dwordx4 v[252:253], off
	s_mov_b32 m0, s63
	s_nop 0
	global_load_lds_dwordx4 v[248:249], off
	v_lshl_add_u64 v[248:249], v[250:251], 0, s[78:79]
	s_mov_b32 m0, s64
	s_nop 0
	global_load_lds_dwordx4 v[248:249], off
	s_waitcnt vmcnt(8)
	s_waitcnt lgkmcnt(0)
	s_barrier
	s_setprio 1
	s_waitcnt lgkmcnt(0)
	v_mfma_f32_16x16x32_bf16 v[62:65], v[130:133], v[216:219], v[62:65]
	v_mfma_f32_16x16x32_bf16 v[58:61], v[138:141], v[216:219], v[58:61]
	v_mfma_f32_16x16x32_bf16 v[46:49], v[130:133], v[224:227], v[46:49]
	v_mfma_f32_16x16x32_bf16 v[42:45], v[138:141], v[224:227], v[42:45]
	v_mfma_f32_16x16x32_bf16 v[30:33], v[130:133], v[232:235], v[30:33]
	v_mfma_f32_16x16x32_bf16 v[26:29], v[138:141], v[232:235], v[26:29]
	v_mfma_f32_16x16x32_bf16 v[14:17], v[130:133], v[240:243], v[14:17]
	v_mfma_f32_16x16x32_bf16 v[10:13], v[138:141], v[240:243], v[10:13]
	v_mfma_f32_16x16x32_bf16 v[62:65], v[134:137], v[220:223], v[62:65]
	v_mfma_f32_16x16x32_bf16 v[58:61], v[154:157], v[220:223], v[58:61]
	v_mfma_f32_16x16x32_bf16 v[46:49], v[134:137], v[228:231], v[46:49]
	v_mfma_f32_16x16x32_bf16 v[42:45], v[154:157], v[228:231], v[42:45]
	v_mfma_f32_16x16x32_bf16 v[30:33], v[134:137], v[236:239], v[30:33]
	v_mfma_f32_16x16x32_bf16 v[26:29], v[154:157], v[236:239], v[26:29]
	v_mfma_f32_16x16x32_bf16 v[14:17], v[134:137], v[244:247], v[14:17]
	v_mfma_f32_16x16x32_bf16 v[10:13], v[154:157], v[244:247], v[10:13]
	s_setprio 0
	s_setprio 1
	v_mfma_f32_16x16x32_bf16 v[54:57], v[176:179], v[216:219], v[54:57]
	v_mfma_f32_16x16x32_bf16 v[50:53], v[184:187], v[216:219], v[50:53]
	v_mfma_f32_16x16x32_bf16 v[38:41], v[176:179], v[224:227], v[38:41]
	v_mfma_f32_16x16x32_bf16 v[34:37], v[184:187], v[224:227], v[34:37]
	v_mfma_f32_16x16x32_bf16 v[22:25], v[176:179], v[232:235], v[22:25]
	v_mfma_f32_16x16x32_bf16 v[18:21], v[184:187], v[232:235], v[18:21]
	v_mfma_f32_16x16x32_bf16 v[6:9], v[176:179], v[240:243], v[6:9]
	v_mfma_f32_16x16x32_bf16 v[2:5], v[184:187], v[240:243], v[2:5]
	v_mfma_f32_16x16x32_bf16 v[54:57], v[180:183], v[220:223], v[54:57]
	v_mfma_f32_16x16x32_bf16 v[50:53], v[188:191], v[220:223], v[50:53]
	v_mfma_f32_16x16x32_bf16 v[38:41], v[180:183], v[228:231], v[38:41]
	v_mfma_f32_16x16x32_bf16 v[34:37], v[188:191], v[228:231], v[34:37]
	v_mfma_f32_16x16x32_bf16 v[22:25], v[180:183], v[236:239], v[22:25]
	v_mfma_f32_16x16x32_bf16 v[18:21], v[188:191], v[236:239], v[18:21]
	v_mfma_f32_16x16x32_bf16 v[6:9], v[180:183], v[244:247], v[6:9]
	v_mfma_f32_16x16x32_bf16 v[2:5], v[188:191], v[244:247], v[2:5]
	s_setprio 0
	s_barrier
	s_add_i32 s43, s43, 2
	s_add_u32 s41, s41, 0x10000
	s_addc_u32 s42, s42, 0
	s_add_u32 s0, s0, 0x100
	s_addc_u32 s1, s1, 0

; #define PG8_STAGE(bufoff, gbase, voff) do { _Pragma("unroll") for (int _i = 0; _i < 2; ++_i) \
;         __builtin_amdgcn_global_load_lds((const unsigned*)((const char*)(gbase) + (voff)[_i]), (PG8_LAS unsigned*)(lds + (bufoff) + ldsw + _i * 8192), 16, 0, 0); } while (0)
; #define PG8_LDA(dst, b, h) do { _Pragma("unroll") for (int m = 0; m < 4; ++m) _Pragma("unroll") for (int k = 0; k < 2; ++k) dst[m][k] = *(const PG8_LAS frag_t*)(lds + PG8_SA(b, h) + aoff + m * 2048 + k * 1024); } while (0)
; #define PG8_LDB(dst, b, h) do { _Pragma("unroll") for (int n = 0; n < 2; ++n) _Pragma("unroll") for (int k = 0; k < 2; ++k) dst[n][k] = *(const PG8_LAS frag_t*)(lds + PG8_SB(b, h) + boff + n * 2048 + k * 1024); } while (0)
; #define PG8_MMA(ai, bj, At, Bt) do { __builtin_amdgcn_s_setprio(1); _Pragma("unroll") for (int m = 0; m < 4; ++m) _Pragma("unroll") for (int n = 0; n < 2; ++n) _Pragma("unroll") for (int k = 0; k < 2; ++k) \
;         acc[ai][bj][m][n] = mma1v<MMAV>(Bt[n][k], At[m][k], acc[ai][bj][m][n]); __builtin_amdgcn_s_setprio(0); } while (0)
; #define PG8_WAIT_V(n) asm volatile("s_waitcnt vmcnt(" #n ")" ::: "memory")
; #define PG8_WAIT_L(n) asm volatile("s_waitcnt lgkmcnt(" #n ")" ::: "memory")
;     ...
;         const bool has_next = S.next(ui + 1, nxt);
;         const char* nA = has_next ? (const char*)g.A + (size_t)nxt.pm * tstep : cA; const char* nB = has_next ? (const char*)g.Bt + (size_t)nxt.pn * tstep : cB;
;         for (int t = 0; t < nt; t += 2) {
;             const bool last = (t == nt - 2);
;             const char* a1 = cA + (size_t)(t + 1) * kstep;
;             const char* a2 = last ? nA : cA + (size_t)(t + 2) * kstep; const char* b2 = last ? nB : cB + (size_t)(t + 2) * kstepB;
;             const char* a3 = a2 + kstep; const char* b3 = b2 + kstepB;
;             if (last && has_next) S.a_ready(nxt);
;             if constexpr (SP2) {
;             PG8_LDB(B0, 0, 0); PG8_LDB(B1, 0, 1); PG8_SCHED; PG8_LDA(At, 0, 0); PG8_STAGE(PG8_SA(1, 1), a1 + hstep, voffA);
;             PG8_WAIT_V(8); PG8_WAIT_L(0); PG8_BAR; PG8_MMA(0, 0, At, B0); PG8_MMA(0, 1, At, B1); PG8_BAR; PG8_SCHED;
;             PG8_LDA(At, 0, 1); PG8_STAGE(PG8_SB(0, 0), b2, voffB); PG8_STAGE(PG8_SB(0, 1), b2 + hstepB, voffB); PG8_STAGE(PG8_SA(0, 0), a2, voffA);
;             PG8_WAIT_V(8); PG8_WAIT_L(0); PG8_BAR; PG8_MMA(1, 0, At, B0); PG8_MMA(1, 1, At, B1); PG8_BAR; PG8_SCHED;
.LBB0_1023:
	s_ashr_i32 s17, s16, 31
	s_lshl_b64 s[18:19], s[16:17], 20
	s_add_u32 s18, s34, s18
	s_addc_u32 s19, s35, s19
	s_and_b64 s[20:21], s[4:5], exec
	s_cselect_b32 s7, s19, s27
	s_cselect_b32 s17, s18, s26
	s_ashr_i32 s15, s14, 31
	s_lshl_b64 s[20:21], s[14:15], 20
	s_add_u32 s20, s36, s20
	s_addc_u32 s21, s37, s21
	s_and_b64 s[28:29], s[4:5], exec
	s_cselect_b32 s15, s21, s25
	s_cselect_b32 s23, s20, s24
	s_add_u32 s51, s24, 0x10000
	s_addc_u32 s52, s25, 0
	s_add_u32 s24, s26, 0x80080
	s_addc_u32 s25, s27, 0
	s_mov_b32 s53, -2
	s_waitcnt lgkmcnt(0)
	s_add_u32 s26, s24, 0xfff80080
	s_addc_u32 s27, s25, -1
	s_add_i32 s54, 0, 0x10000
	s_cmp_eq_u32 s53, 28
	s_cselect_b32 s29, s7, s27
	s_cselect_b32 s28, s17, s26
	v_add_u32_e32 v148, s54, v151
	s_cselect_b32 s27, s15, s52
	s_cselect_b32 s26, s23, s51
	s_add_i32 s56, 0, 0x14000
	ds_read_b128 v[130:133], v148
	ds_read_b128 v[134:137], v148 offset:1024
	ds_read_b128 v[154:157], v148 offset:2048
	ds_read_b128 v[158:161], v148 offset:3072
	v_add_u32_e32 v148, s56, v151
	ds_read_b128 v[174:177], v148
	ds_read_b128 v[178:181], v148 offset:1024
	ds_read_b128 v[182:185], v148 offset:2048
	ds_read_b128 v[186:189], v148 offset:3072
	v_lshl_add_u64 v[148:149], s[24:25], 0, v[144:145]
	s_add_i32 m0, s39, 0xc000
	ds_read_b128 v[216:219], v152
	ds_read_b128 v[220:223], v152 offset:1024
	ds_read_b128 v[224:227], v152 offset:2048
	ds_read_b128 v[228:231], v152 offset:3072
	ds_read_b128 v[232:235], v152 offset:4096
	ds_read_b128 v[236:239], v152 offset:5120
	ds_read_b128 v[240:243], v152 offset:6144
	ds_read_b128 v[244:247], v152 offset:7168
	global_load_lds_dwordx4 v[148:149], off
	v_lshl_add_u64 v[148:149], s[24:25], 0, v[146:147]
	s_add_i32 m0, s39, 0xe000
	s_nop 0
	global_load_lds_dwordx4 v[148:149], off
	s_waitcnt vmcnt(24)
	s_waitcnt lgkmcnt(0)
	s_barrier
	s_setprio 1
	s_waitcnt lgkmcnt(0)
	v_mfma_f32_16x16x32_bf16 v[126:129], v[130:133], v[216:219], 0
	v_mfma_f32_16x16x32_bf16 v[122:125], v[154:157], v[216:219], 0
	v_mfma_f32_16x16x32_bf16 v[110:113], v[130:133], v[224:227], 0
	v_mfma_f32_16x16x32_bf16 v[106:109], v[154:157], v[224:227], 0
	v_mfma_f32_16x16x32_bf16 v[94:97], v[130:133], v[232:235], 0
	v_mfma_f32_16x16x32_bf16 v[90:93], v[154:157], v[232:235], 0
	v_mfma_f32_16x16x32_bf16 v[78:81], v[130:133], v[240:243], 0
	v_mfma_f32_16x16x32_bf16 v[74:77], v[154:157], v[240:243], 0
	v_mfma_f32_16x16x32_bf16 v[126:129], v[134:137], v[220:223], v[126:129]
	v_mfma_f32_16x16x32_bf16 v[122:125], v[158:161], v[220:223], v[122:125]
	v_mfma_f32_16x16x32_bf16 v[110:113], v[134:137], v[228:231], v[110:113]
	v_mfma_f32_16x16x32_bf16 v[106:109], v[158:161], v[228:231], v[106:109]
	v_mfma_f32_16x16x32_bf16 v[94:97], v[134:137], v[236:239], v[94:97]
	v_mfma_f32_16x16x32_bf16 v[90:93], v[158:161], v[236:239], v[90:93]
	v_mfma_f32_16x16x32_bf16 v[78:81], v[134:137], v[244:247], v[78:81]
	v_mfma_f32_16x16x32_bf16 v[74:77], v[158:161], v[244:247], v[74:77]
	s_setprio 0
	s_setprio 1
	v_mfma_f32_16x16x32_bf16 v[118:121], v[174:177], v[216:219], 0
	v_mfma_f32_16x16x32_bf16 v[114:117], v[182:185], v[216:219], 0
	v_mfma_f32_16x16x32_bf16 v[102:105], v[174:177], v[224:227], 0
	v_mfma_f32_16x16x32_bf16 v[98:101], v[182:185], v[224:227], 0
	v_mfma_f32_16x16x32_bf16 v[86:89], v[174:177], v[232:235], 0
	v_mfma_f32_16x16x32_bf16 v[82:85], v[182:185], v[232:235], 0
	v_mfma_f32_16x16x32_bf16 v[70:73], v[174:177], v[240:243], 0
	v_mfma_f32_16x16x32_bf16 v[66:69], v[182:185], v[240:243], 0
	v_mfma_f32_16x16x32_bf16 v[118:121], v[178:181], v[220:223], v[118:121]
	v_mfma_f32_16x16x32_bf16 v[114:117], v[186:189], v[220:223], v[114:117]
	v_mfma_f32_16x16x32_bf16 v[102:105], v[178:181], v[228:231], v[102:105]
	v_mfma_f32_16x16x32_bf16 v[98:101], v[186:189], v[228:231], v[98:101]
	v_mfma_f32_16x16x32_bf16 v[86:89], v[178:181], v[236:239], v[86:89]
	v_mfma_f32_16x16x32_bf16 v[82:85], v[186:189], v[236:239], v[82:85]
	v_mfma_f32_16x16x32_bf16 v[70:73], v[178:181], v[244:247], v[70:73]
	v_mfma_f32_16x16x32_bf16 v[66:69], v[186:189], v[244:247], v[66:69]
	s_setprio 0
	s_barrier
	s_add_i32 s54, s54, s38
	v_lshl_add_u64 v[148:149], s[26:27], 0, v[138:139]
	s_mov_b32 m0, s54
	ds_read_b128 v[216:219], v152 offset:16384
	ds_read_b128 v[220:223], v152 offset:17408
	ds_read_b128 v[224:227], v152 offset:18432
	ds_read_b128 v[228:231], v152 offset:19456
	ds_read_b128 v[232:235], v152 offset:20480
	ds_read_b128 v[236:239], v152 offset:21504
	ds_read_b128 v[240:243], v152 offset:22528
	ds_read_b128 v[244:247], v152 offset:23552
	global_load_lds_dwordx4 v[148:149], off
	s_add_i32 m0, s54, 0x2000
	s_add_u32 s54, s26, 0x4000
	v_lshl_add_u64 v[148:149], s[26:27], 0, v[142:143]
	s_addc_u32 s55, s27, 0
	s_add_i32 s56, s56, s38
	global_load_lds_dwordx4 v[148:149], off
	v_lshl_add_u64 v[148:149], s[54:55], 0, v[138:139]
	s_mov_b32 m0, s56
	v_lshl_add_u64 v[190:191], s[28:29], 0, v[140:141]
	global_load_lds_dwordx4 v[148:149], off
	v_lshl_add_u64 v[148:149], s[54:55], 0, v[142:143]
	s_add_i32 m0, s56, 0x2000
	s_nop 0
	global_load_lds_dwordx4 v[148:149], off
	v_lshl_add_u64 v[148:149], s[28:29], 0, v[162:163]
	s_mov_b32 m0, s39
	s_nop 0
	global_load_lds_dwordx4 v[148:149], off
	s_mov_b32 m0, s40
	s_nop 0
	global_load_lds_dwordx4 v[190:191], off
	s_waitcnt vmcnt(8)
	s_waitcnt lgkmcnt(0)
	s_barrier
; #define PG8_STAGE(bufoff, gbase, voff) do { _Pragma("unroll") for (int _i = 0; _i < 2; ++_i) \
;         __builtin_amdgcn_global_load_lds((const unsigned*)((const char*)(gbase) + (voff)[_i]), (PG8_LAS unsigned*)(lds + (bufoff) + ldsw + _i * 8192), 16, 0, 0); } while (0)
; #define PG8_LDA(dst, b, h) do { _Pragma("unroll") for (int m = 0; m < 4; ++m) _Pragma("unroll") for (int k = 0; k < 2; ++k) dst[m][k] = *(const PG8_LAS frag_t*)(lds + PG8_SA(b, h) + aoff + m * 2048 + k * 1024); } while (0)
; #define PG8_LDB(dst, b, h) do { _Pragma("unroll") for (int n = 0; n < 2; ++n) _Pragma("unroll") for (int k = 0; k < 2; ++k) dst[n][k] = *(const PG8_LAS frag_t*)(lds + PG8_SB(b, h) + boff + n * 2048 + k * 1024); } while (0)
; #define PG8_MMA(ai, bj, At, Bt) do { __builtin_amdgcn_s_setprio(1); _Pragma("unroll") for (int m = 0; m < 4; ++m) _Pragma("unroll") for (int n = 0; n < 2; ++n) _Pragma("unroll") for (int k = 0; k < 2; ++k) \
;         acc[ai][bj][m][n] = mma1v<MMAV>(Bt[n][k], At[m][k], acc[ai][bj][m][n]); __builtin_amdgcn_s_setprio(0); } while (0)
; #define PG8_WAIT_V(n) asm volatile("s_waitcnt vmcnt(" #n ")" ::: "memory")
; #define PG8_WAIT_L(n) asm volatile("s_waitcnt lgkmcnt(" #n ")" ::: "memory")
; #define PG8_BAR __builtin_amdgcn_s_barrier()
; #define PG8_SCHED __builtin_amdgcn_sched_barrier(0)
;     ...
;             PG8_WAIT_V(8); PG8_WAIT_L(0); PG8_BAR; PG8_MMA(1, 0, At, B0); PG8_MMA(1, 1, At, B1); PG8_BAR; PG8_SCHED;
;             PG8_LDB(B0, 1, 0); PG8_LDB(B1, 1, 1); PG8_SCHED; PG8_LDA(At, 1, 0); PG8_STAGE(PG8_SA(0, 1), a2 + hstep, voffA);
;             PG8_WAIT_V(8); PG8_WAIT_L(0); PG8_BAR; PG8_MMA(0, 0, At, B0); PG8_MMA(0, 1, At, B1); PG8_BAR; PG8_SCHED;
;             PG8_LDA(At, 1, 1); PG8_STAGE(PG8_SB(1, 0), b3, voffB); PG8_STAGE(PG8_SB(1, 1), b3 + hstepB, voffB); PG8_STAGE(PG8_SA(1, 0), a3, voffA);
;             PG8_WAIT_V(8); PG8_WAIT_L(0); PG8_BAR; PG8_MMA(1, 0, At, B0); PG8_MMA(1, 1, At, B1); PG8_BAR; PG8_SCHED;
	s_setprio 1
	s_waitcnt lgkmcnt(0)
	v_mfma_f32_16x16x32_bf16 v[62:65], v[130:133], v[216:219], 0
	v_mfma_f32_16x16x32_bf16 v[58:61], v[154:157], v[216:219], 0
	v_mfma_f32_16x16x32_bf16 v[46:49], v[130:133], v[224:227], 0
	v_mfma_f32_16x16x32_bf16 v[42:45], v[154:157], v[224:227], 0
	v_mfma_f32_16x16x32_bf16 v[30:33], v[130:133], v[232:235], 0
	v_mfma_f32_16x16x32_bf16 v[26:29], v[154:157], v[232:235], 0
	v_mfma_f32_16x16x32_bf16 v[14:17], v[130:133], v[240:243], 0
	v_mfma_f32_16x16x32_bf16 v[10:13], v[154:157], v[240:243], 0
	v_mfma_f32_16x16x32_bf16 v[62:65], v[134:137], v[220:223], v[62:65]
	v_mfma_f32_16x16x32_bf16 v[58:61], v[158:161], v[220:223], v[58:61]
	v_mfma_f32_16x16x32_bf16 v[46:49], v[134:137], v[228:231], v[46:49]
	v_mfma_f32_16x16x32_bf16 v[42:45], v[158:161], v[228:231], v[42:45]
	v_mfma_f32_16x16x32_bf16 v[30:33], v[134:137], v[236:239], v[30:33]
	v_mfma_f32_16x16x32_bf16 v[26:29], v[158:161], v[236:239], v[26:29]
	v_mfma_f32_16x16x32_bf16 v[14:17], v[134:137], v[244:247], v[14:17]
	v_mfma_f32_16x16x32_bf16 v[10:13], v[158:161], v[244:247], v[10:13]
	s_setprio 0
	s_setprio 1
	v_mfma_f32_16x16x32_bf16 v[54:57], v[174:177], v[216:219], 0
	v_mfma_f32_16x16x32_bf16 v[50:53], v[182:185], v[216:219], 0
	v_mfma_f32_16x16x32_bf16 v[38:41], v[174:177], v[224:227], 0
	v_mfma_f32_16x16x32_bf16 v[34:37], v[182:185], v[224:227], 0
	v_mfma_f32_16x16x32_bf16 v[22:25], v[174:177], v[232:235], 0
	v_mfma_f32_16x16x32_bf16 v[18:21], v[182:185], v[232:235], 0
	v_mfma_f32_16x16x32_bf16 v[6:9], v[174:177], v[240:243], 0
	v_mfma_f32_16x16x32_bf16 v[2:5], v[182:185], v[240:243], 0
	v_mfma_f32_16x16x32_bf16 v[54:57], v[178:181], v[220:223], v[54:57]
	v_mfma_f32_16x16x32_bf16 v[50:53], v[186:189], v[220:223], v[50:53]
	v_mfma_f32_16x16x32_bf16 v[38:41], v[178:181], v[228:231], v[38:41]
	v_mfma_f32_16x16x32_bf16 v[34:37], v[186:189], v[228:231], v[34:37]
	v_mfma_f32_16x16x32_bf16 v[22:25], v[178:181], v[236:239], v[22:25]
	v_mfma_f32_16x16x32_bf16 v[18:21], v[186:189], v[236:239], v[18:21]
	v_mfma_f32_16x16x32_bf16 v[6:9], v[178:181], v[244:247], v[6:9]
	v_mfma_f32_16x16x32_bf16 v[2:5], v[186:189], v[244:247], v[2:5]
	s_setprio 0
	s_barrier
	s_add_i32 s54, 0, 0x18000
	v_add_u32_e32 v153, s54, v151
	s_add_i32 s55, 0, 0x1c000
	ds_read_b128 v[130:133], v153
	ds_read_b128 v[134:137], v153 offset:1024
	ds_read_b128 v[154:157], v153 offset:2048
	ds_read_b128 v[158:161], v153 offset:3072
	v_add_u32_e32 v153, s55, v151
	ds_read_b128 v[174:177], v153
	ds_read_b128 v[178:181], v153 offset:1024
	ds_read_b128 v[182:185], v153 offset:2048
	ds_read_b128 v[186:189], v153 offset:3072
	s_add_u32 s28, s28, 0x80000
	s_addc_u32 s29, s29, 0
	s_mov_b32 m0, s41
	v_lshl_add_u64 v[248:249], s[28:29], 0, v[162:163]
	ds_read_b128 v[216:219], v152 offset:32768
	ds_read_b128 v[220:223], v152 offset:33792
	ds_read_b128 v[224:227], v152 offset:34816
	ds_read_b128 v[228:231], v152 offset:35840
	ds_read_b128 v[232:235], v152 offset:36864
	ds_read_b128 v[236:239], v152 offset:37888
	ds_read_b128 v[240:243], v152 offset:38912
	ds_read_b128 v[244:247], v152 offset:39936
	global_load_lds_dwordx4 v[248:249], off
	v_lshl_add_u64 v[248:249], s[28:29], 0, v[140:141]
	s_mov_b32 m0, s42
	s_nop 0
	global_load_lds_dwordx4 v[248:249], off
	s_waitcnt vmcnt(8)
	s_waitcnt lgkmcnt(0)
	s_barrier
	s_setprio 1
	s_waitcnt lgkmcnt(0)
	v_mfma_f32_16x16x32_bf16 v[126:129], v[130:133], v[216:219], v[126:129]
	v_mfma_f32_16x16x32_bf16 v[122:125], v[154:157], v[216:219], v[122:125]
	v_mfma_f32_16x16x32_bf16 v[110:113], v[130:133], v[224:227], v[110:113]
	v_mfma_f32_16x16x32_bf16 v[106:109], v[154:157], v[224:227], v[106:109]
	v_mfma_f32_16x16x32_bf16 v[94:97], v[130:133], v[232:235], v[94:97]
	v_mfma_f32_16x16x32_bf16 v[90:93], v[154:157], v[232:235], v[90:93]
	v_mfma_f32_16x16x32_bf16 v[78:81], v[130:133], v[240:243], v[78:81]
	v_mfma_f32_16x16x32_bf16 v[74:77], v[154:157], v[240:243], v[74:77]
	v_mfma_f32_16x16x32_bf16 v[126:129], v[134:137], v[220:223], v[126:129]
	v_mfma_f32_16x16x32_bf16 v[122:125], v[158:161], v[220:223], v[122:125]
	v_mfma_f32_16x16x32_bf16 v[110:113], v[134:137], v[228:231], v[110:113]
	v_mfma_f32_16x16x32_bf16 v[106:109], v[158:161], v[228:231], v[106:109]
	v_mfma_f32_16x16x32_bf16 v[94:97], v[134:137], v[236:239], v[94:97]
	v_mfma_f32_16x16x32_bf16 v[90:93], v[158:161], v[236:239], v[90:93]
	v_mfma_f32_16x16x32_bf16 v[78:81], v[134:137], v[244:247], v[78:81]
	v_mfma_f32_16x16x32_bf16 v[74:77], v[158:161], v[244:247], v[74:77]
	s_setprio 0
	s_setprio 1
	v_mfma_f32_16x16x32_bf16 v[118:121], v[174:177], v[216:219], v[118:121]
	v_mfma_f32_16x16x32_bf16 v[114:117], v[182:185], v[216:219], v[114:117]
	v_mfma_f32_16x16x32_bf16 v[102:105], v[174:177], v[224:227], v[102:105]
	v_mfma_f32_16x16x32_bf16 v[98:101], v[182:185], v[224:227], v[98:101]
	v_mfma_f32_16x16x32_bf16 v[86:89], v[174:177], v[232:235], v[86:89]
	v_mfma_f32_16x16x32_bf16 v[82:85], v[182:185], v[232:235], v[82:85]
	v_mfma_f32_16x16x32_bf16 v[70:73], v[174:177], v[240:243], v[70:73]
	v_mfma_f32_16x16x32_bf16 v[66:69], v[182:185], v[240:243], v[66:69]
	v_mfma_f32_16x16x32_bf16 v[118:121], v[178:181], v[220:223], v[118:121]
	v_mfma_f32_16x16x32_bf16 v[114:117], v[186:189], v[220:223], v[114:117]
	v_mfma_f32_16x16x32_bf16 v[102:105], v[178:181], v[228:231], v[102:105]
	v_mfma_f32_16x16x32_bf16 v[98:101], v[186:189], v[228:231], v[98:101]
	v_mfma_f32_16x16x32_bf16 v[86:89], v[178:181], v[236:239], v[86:89]
	v_mfma_f32_16x16x32_bf16 v[82:85], v[186:189], v[236:239], v[82:85]
	v_mfma_f32_16x16x32_bf16 v[70:73], v[178:181], v[244:247], v[70:73]
	v_mfma_f32_16x16x32_bf16 v[66:69], v[186:189], v[244:247], v[66:69]
	s_setprio 0
	s_barrier
; #define PG8_STAGE(bufoff, gbase, voff) do { _Pragma("unroll") for (int _i = 0; _i < 2; ++_i) \
;         __builtin_amdgcn_global_load_lds((const unsigned*)((const char*)(gbase) + (voff)[_i]), (PG8_LAS unsigned*)(lds + (bufoff) + ldsw + _i * 8192), 16, 0, 0); } while (0)
; #define PG8_LDA(dst, b, h) do { _Pragma("unroll") for (int m = 0; m < 4; ++m) _Pragma("unroll") for (int k = 0; k < 2; ++k) dst[m][k] = *(const PG8_LAS frag_t*)(lds + PG8_SA(b, h) + aoff + m * 2048 + k * 1024); } while (0)
; #define PG8_MMA(ai, bj, At, Bt) do { __builtin_amdgcn_s_setprio(1); _Pragma("unroll") for (int m = 0; m < 4; ++m) _Pragma("unroll") for (int n = 0; n < 2; ++n) _Pragma("unroll") for (int k = 0; k < 2; ++k) \
;         acc[ai][bj][m][n] = mma1v<MMAV>(Bt[n][k], At[m][k], acc[ai][bj][m][n]); __builtin_amdgcn_s_setprio(0); } while (0)
; #define PG8_WAIT_V(n) asm volatile("s_waitcnt vmcnt(" #n ")" ::: "memory")
; #define PG8_WAIT_L(n) asm volatile("s_waitcnt lgkmcnt(" #n ")" ::: "memory")
; #define PG8_BAR __builtin_amdgcn_s_barrier()
; #define PG8_SCHED __builtin_amdgcn_sched_barrier(0)
;     ...
;             PG8_WAIT_V(8); PG8_WAIT_L(0); PG8_BAR; PG8_MMA(0, 0, At, B0); PG8_MMA(0, 1, At, B1); PG8_BAR; PG8_SCHED;
;             PG8_LDA(At, 1, 1); PG8_STAGE(PG8_SB(1, 0), b3, voffB); PG8_STAGE(PG8_SB(1, 1), b3 + hstepB, voffB); PG8_STAGE(PG8_SA(1, 0), a3, voffA);
;             PG8_WAIT_V(8); PG8_WAIT_L(0); PG8_BAR; PG8_MMA(1, 0, At, B0); PG8_MMA(1, 1, At, B1); PG8_BAR; PG8_SCHED;
	s_add_u32 s28, s26, 0x8000
	s_addc_u32 s29, s27, 0
	s_add_i32 s54, s54, s38
	v_lshl_add_u64 v[248:249], s[28:29], 0, v[138:139]
	s_mov_b32 m0, s54
	ds_read_b128 v[216:219], v152 offset:49152
	ds_read_b128 v[220:223], v152 offset:50176
	ds_read_b128 v[224:227], v152 offset:51200
	ds_read_b128 v[228:231], v152 offset:52224
	ds_read_b128 v[232:235], v152 offset:53248
	ds_read_b128 v[236:239], v152 offset:54272
	ds_read_b128 v[240:243], v152 offset:55296
	ds_read_b128 v[244:247], v152 offset:56320
	global_load_lds_dwordx4 v[248:249], off
	s_add_i32 m0, s54, 0x2000
	s_add_u32 s26, s26, 0xc000
	v_lshl_add_u64 v[248:249], s[28:29], 0, v[142:143]
	s_addc_u32 s27, s27, 0
	s_add_i32 s28, s55, s38
	global_load_lds_dwordx4 v[248:249], off
	v_lshl_add_u64 v[248:249], s[26:27], 0, v[138:139]
	s_mov_b32 m0, s28
	v_lshl_add_u64 v[148:149], v[148:149], 0, s[78:79]
	global_load_lds_dwordx4 v[248:249], off
	v_lshl_add_u64 v[248:249], s[26:27], 0, v[142:143]
	s_add_i32 m0, s28, 0x2000
	s_nop 0
	global_load_lds_dwordx4 v[248:249], off
	s_mov_b32 m0, s46
	s_nop 0
	global_load_lds_dwordx4 v[148:149], off
	v_lshl_add_u64 v[148:149], v[190:191], 0, s[78:79]
	s_mov_b32 m0, s47
	s_nop 0
	global_load_lds_dwordx4 v[148:149], off
	s_waitcnt vmcnt(8)
	s_waitcnt lgkmcnt(0)
	s_barrier
	s_setprio 1
	s_waitcnt lgkmcnt(0)
	v_mfma_f32_16x16x32_bf16 v[62:65], v[130:133], v[216:219], v[62:65]
	v_mfma_f32_16x16x32_bf16 v[58:61], v[154:157], v[216:219], v[58:61]
	v_mfma_f32_16x16x32_bf16 v[46:49], v[130:133], v[224:227], v[46:49]
	v_mfma_f32_16x16x32_bf16 v[42:45], v[154:157], v[224:227], v[42:45]
	v_mfma_f32_16x16x32_bf16 v[30:33], v[130:133], v[232:235], v[30:33]
	v_mfma_f32_16x16x32_bf16 v[26:29], v[154:157], v[232:235], v[26:29]
	v_mfma_f32_16x16x32_bf16 v[14:17], v[130:133], v[240:243], v[14:17]
	v_mfma_f32_16x16x32_bf16 v[10:13], v[154:157], v[240:243], v[10:13]
	v_mfma_f32_16x16x32_bf16 v[62:65], v[134:137], v[220:223], v[62:65]
	v_mfma_f32_16x16x32_bf16 v[58:61], v[158:161], v[220:223], v[58:61]
	v_mfma_f32_16x16x32_bf16 v[46:49], v[134:137], v[228:231], v[46:49]
	v_mfma_f32_16x16x32_bf16 v[42:45], v[158:161], v[228:231], v[42:45]
	v_mfma_f32_16x16x32_bf16 v[30:33], v[134:137], v[236:239], v[30:33]
	v_mfma_f32_16x16x32_bf16 v[26:29], v[158:161], v[236:239], v[26:29]
	v_mfma_f32_16x16x32_bf16 v[14:17], v[134:137], v[244:247], v[14:17]
	v_mfma_f32_16x16x32_bf16 v[10:13], v[158:161], v[244:247], v[10:13]
	s_setprio 0
	s_setprio 1
	v_mfma_f32_16x16x32_bf16 v[54:57], v[174:177], v[216:219], v[54:57]
	v_mfma_f32_16x16x32_bf16 v[50:53], v[182:185], v[216:219], v[50:53]
	v_mfma_f32_16x16x32_bf16 v[38:41], v[174:177], v[224:227], v[38:41]
	v_mfma_f32_16x16x32_bf16 v[34:37], v[182:185], v[224:227], v[34:37]
	v_mfma_f32_16x16x32_bf16 v[22:25], v[174:177], v[232:235], v[22:25]
	v_mfma_f32_16x16x32_bf16 v[18:21], v[182:185], v[232:235], v[18:21]
	v_mfma_f32_16x16x32_bf16 v[6:9], v[174:177], v[240:243], v[6:9]
	v_mfma_f32_16x16x32_bf16 v[2:5], v[182:185], v[240:243], v[2:5]
	v_mfma_f32_16x16x32_bf16 v[54:57], v[178:181], v[220:223], v[54:57]
	v_mfma_f32_16x16x32_bf16 v[50:53], v[186:189], v[220:223], v[50:53]
	v_mfma_f32_16x16x32_bf16 v[38:41], v[178:181], v[228:231], v[38:41]
	v_mfma_f32_16x16x32_bf16 v[34:37], v[186:189], v[228:231], v[34:37]
	v_mfma_f32_16x16x32_bf16 v[22:25], v[178:181], v[236:239], v[22:25]
	v_mfma_f32_16x16x32_bf16 v[18:21], v[186:189], v[236:239], v[18:21]
	v_mfma_f32_16x16x32_bf16 v[6:9], v[178:181], v[244:247], v[6:9]
	v_mfma_f32_16x16x32_bf16 v[2:5], v[186:189], v[244:247], v[2:5]
	s_setprio 0
	s_barrier
	s_add_i32 s53, s53, 2
	s_add_u32 s51, s51, 0x10000
	s_addc_u32 s52, s52, 0
	s_add_u32 s24, s24, 0x100
	s_addc_u32 s25, s25, 0

; #define PG8_STAGE(bufoff, gbase, voff) do { _Pragma("unroll") for (int _i = 0; _i < 2; ++_i) \
;         __builtin_amdgcn_global_load_lds((const unsigned*)((const char*)(gbase) + (voff)[_i]), (PG8_LAS unsigned*)(lds + (bufoff) + ldsw + _i * 8192), 16, 0, 0); } while (0)
; #define PG8_LDA(dst, b, h) do { _Pragma("unroll") for (int m = 0; m < 4; ++m) _Pragma("unroll") for (int k = 0; k < 2; ++k) dst[m][k] = *(const PG8_LAS frag_t*)(lds + PG8_SA(b, h) + aoff + m * 2048 + k * 1024); } while (0)
; #define PG8_LDB(dst, b, h) do { _Pragma("unroll") for (int n = 0; n < 2; ++n) _Pragma("unroll") for (int k = 0; k < 2; ++k) dst[n][k] = *(const PG8_LAS frag_t*)(lds + PG8_SB(b, h) + boff + n * 2048 + k * 1024); } while (0)
; #define PG8_MMA(ai, bj, At, Bt) do { __builtin_amdgcn_s_setprio(1); _Pragma("unroll") for (int m = 0; m < 4; ++m) _Pragma("unroll") for (int n = 0; n < 2; ++n) _Pragma("unroll") for (int k = 0; k < 2; ++k) \
;         acc[ai][bj][m][n] = mma1v<MMAV>(Bt[n][k], At[m][k], acc[ai][bj][m][n]); __builtin_amdgcn_s_setprio(0); } while (0)
; #define PG8_WAIT_V(n) asm volatile("s_waitcnt vmcnt(" #n ")" ::: "memory")
; #define PG8_WAIT_L(n) asm volatile("s_waitcnt lgkmcnt(" #n ")" ::: "memory")
;     ...
;         const bool has_next = S.next(ui + 1, nxt);
;         const char* nA = has_next ? (const char*)g.A + (size_t)nxt.pm * tstep : cA; const char* nB = has_next ? (const char*)g.Bt + (size_t)nxt.pn * tstep : cB;
;         for (int t = 0; t < nt; t += 2) {
;             const bool last = (t == nt - 2);
;             const char* a1 = cA + (size_t)(t + 1) * kstep;
;             const char* a2 = last ? nA : cA + (size_t)(t + 2) * kstep; const char* b2 = last ? nB : cB + (size_t)(t + 2) * kstepB;
;             const char* a3 = a2 + kstep; const char* b3 = b2 + kstepB;
;             if (last && has_next) S.a_ready(nxt);
;             if constexpr (SP2) {
;             PG8_LDB(B0, 0, 0); PG8_LDB(B1, 0, 1); PG8_SCHED; PG8_LDA(At, 0, 0); PG8_STAGE(PG8_SA(1, 1), a1 + hstep, voffA);
;             PG8_WAIT_V(8); PG8_WAIT_L(0); PG8_BAR; PG8_MMA(0, 0, At, B0); PG8_MMA(0, 1, At, B1); PG8_BAR; PG8_SCHED;
;             PG8_LDA(At, 0, 1); PG8_STAGE(PG8_SB(0, 0), b2, voffB); PG8_STAGE(PG8_SB(0, 1), b2 + hstepB, voffB); PG8_STAGE(PG8_SA(0, 0), a2, voffA);
;             PG8_WAIT_V(8); PG8_WAIT_L(0); PG8_BAR; PG8_MMA(1, 0, At, B0); PG8_MMA(1, 1, At, B1); PG8_BAR; PG8_SCHED;
.LBB0_1223:
	s_add_u32 s6, s20, 0xc000
	s_addc_u32 s7, s21, 0
	s_add_u32 s49, s18, 0x10000
	s_addc_u32 s50, s19, 0
	s_mov_b32 s51, -2
	s_waitcnt lgkmcnt(0)
	s_add_u32 s18, s6, 0x4000
	s_addc_u32 s19, s7, 0
	s_cmpk_eq_i32 s51, 0x54
	s_cselect_b32 s22, s14, s18
	s_cselect_b32 s23, s15, s19
	s_cselect_b32 s20, s16, s49
	s_cselect_b32 s21, s17, s50
	s_add_u32 s18, s22, 0x8000
	s_addc_u32 s19, s23, 0
	s_add_i32 s52, 0, 0x10000
	v_add_u32_e32 v148, s52, v151
	s_add_i32 s54, 0, 0x14000
	ds_read_b128 v[130:133], v148
	ds_read_b128 v[134:137], v148 offset:1024
	ds_read_b128 v[154:157], v148 offset:2048
	ds_read_b128 v[158:161], v148 offset:3072
	v_add_u32_e32 v148, s54, v151
	ds_read_b128 v[174:177], v148
	ds_read_b128 v[178:181], v148 offset:1024
	ds_read_b128 v[182:185], v148 offset:2048
	ds_read_b128 v[186:189], v148 offset:3072
	v_lshl_add_u64 v[148:149], s[6:7], 0, v[144:145]
	s_add_i32 m0, s31, 0xc000
	ds_read_b128 v[216:219], v152
	ds_read_b128 v[220:223], v152 offset:1024
	ds_read_b128 v[224:227], v152 offset:2048
	ds_read_b128 v[228:231], v152 offset:3072
	ds_read_b128 v[232:235], v152 offset:4096
	ds_read_b128 v[236:239], v152 offset:5120
	ds_read_b128 v[240:243], v152 offset:6144
	ds_read_b128 v[244:247], v152 offset:7168
	global_load_lds_dwordx4 v[148:149], off
	v_lshl_add_u64 v[148:149], s[6:7], 0, v[146:147]
	s_add_i32 m0, s31, 0xe000
	s_nop 0
	global_load_lds_dwordx4 v[148:149], off
	s_waitcnt vmcnt(24)
	s_waitcnt lgkmcnt(0)
	s_barrier
	s_setprio 1
	s_waitcnt lgkmcnt(0)
	v_mfma_f32_16x16x32_bf16 v[126:129], v[130:133], v[216:219], 0
	v_mfma_f32_16x16x32_bf16 v[122:125], v[154:157], v[216:219], 0
	v_mfma_f32_16x16x32_bf16 v[110:113], v[130:133], v[224:227], 0
	v_mfma_f32_16x16x32_bf16 v[106:109], v[154:157], v[224:227], 0
	v_mfma_f32_16x16x32_bf16 v[94:97], v[130:133], v[232:235], 0
	v_mfma_f32_16x16x32_bf16 v[90:93], v[154:157], v[232:235], 0
	v_mfma_f32_16x16x32_bf16 v[78:81], v[130:133], v[240:243], 0
	v_mfma_f32_16x16x32_bf16 v[74:77], v[154:157], v[240:243], 0
	v_mfma_f32_16x16x32_bf16 v[126:129], v[134:137], v[220:223], v[126:129]
	v_mfma_f32_16x16x32_bf16 v[122:125], v[158:161], v[220:223], v[122:125]
	v_mfma_f32_16x16x32_bf16 v[110:113], v[134:137], v[228:231], v[110:113]
	v_mfma_f32_16x16x32_bf16 v[106:109], v[158:161], v[228:231], v[106:109]
	v_mfma_f32_16x16x32_bf16 v[94:97], v[134:137], v[236:239], v[94:97]
	v_mfma_f32_16x16x32_bf16 v[90:93], v[158:161], v[236:239], v[90:93]
	v_mfma_f32_16x16x32_bf16 v[78:81], v[134:137], v[244:247], v[78:81]
	v_mfma_f32_16x16x32_bf16 v[74:77], v[158:161], v[244:247], v[74:77]
	s_setprio 0
	s_setprio 1
	v_mfma_f32_16x16x32_bf16 v[118:121], v[174:177], v[216:219], 0
	v_mfma_f32_16x16x32_bf16 v[114:117], v[182:185], v[216:219], 0
	v_mfma_f32_16x16x32_bf16 v[102:105], v[174:177], v[224:227], 0
	v_mfma_f32_16x16x32_bf16 v[98:101], v[182:185], v[224:227], 0
	v_mfma_f32_16x16x32_bf16 v[86:89], v[174:177], v[232:235], 0
	v_mfma_f32_16x16x32_bf16 v[82:85], v[182:185], v[232:235], 0
	v_mfma_f32_16x16x32_bf16 v[70:73], v[174:177], v[240:243], 0
	v_mfma_f32_16x16x32_bf16 v[66:69], v[182:185], v[240:243], 0
	v_mfma_f32_16x16x32_bf16 v[118:121], v[178:181], v[220:223], v[118:121]
	v_mfma_f32_16x16x32_bf16 v[114:117], v[186:189], v[220:223], v[114:117]
	v_mfma_f32_16x16x32_bf16 v[102:105], v[178:181], v[228:231], v[102:105]
	v_mfma_f32_16x16x32_bf16 v[98:101], v[186:189], v[228:231], v[98:101]
	v_mfma_f32_16x16x32_bf16 v[86:89], v[178:181], v[236:239], v[86:89]
	v_mfma_f32_16x16x32_bf16 v[82:85], v[186:189], v[236:239], v[82:85]
	v_mfma_f32_16x16x32_bf16 v[70:73], v[178:181], v[244:247], v[70:73]
	v_mfma_f32_16x16x32_bf16 v[66:69], v[186:189], v[244:247], v[66:69]
	s_setprio 0
	s_barrier
	s_add_i32 s52, s52, s30
	v_lshl_add_u64 v[148:149], s[20:21], 0, v[162:163]
	s_mov_b32 m0, s52
	ds_read_b128 v[216:219], v152 offset:16384
	ds_read_b128 v[220:223], v152 offset:17408
	ds_read_b128 v[224:227], v152 offset:18432
	ds_read_b128 v[228:231], v152 offset:19456
	ds_read_b128 v[232:235], v152 offset:20480
	ds_read_b128 v[236:239], v152 offset:21504
	ds_read_b128 v[240:243], v152 offset:22528
	ds_read_b128 v[244:247], v152 offset:23552
	global_load_lds_dwordx4 v[148:149], off
	s_add_i32 m0, s52, 0x2000
	s_add_u32 s52, s20, 0x4000
	v_lshl_add_u64 v[148:149], s[20:21], 0, v[142:143]
	s_addc_u32 s53, s21, 0
	s_add_i32 s54, s54, s30
	global_load_lds_dwordx4 v[148:149], off
	v_lshl_add_u64 v[148:149], s[52:53], 0, v[162:163]
	s_mov_b32 m0, s54
	s_nop 0
	global_load_lds_dwordx4 v[148:149], off
	v_lshl_add_u64 v[148:149], s[52:53], 0, v[142:143]
	s_add_i32 m0, s54, 0x2000
	s_nop 0
	global_load_lds_dwordx4 v[148:149], off
	v_lshl_add_u64 v[148:149], s[22:23], 0, v[138:139]
	s_mov_b32 m0, s31
	s_nop 0
	global_load_lds_dwordx4 v[148:149], off
	v_lshl_add_u64 v[148:149], s[22:23], 0, v[140:141]
	s_mov_b32 m0, s34
	s_nop 0
	global_load_lds_dwordx4 v[148:149], off
	s_waitcnt vmcnt(8)
	s_waitcnt lgkmcnt(0)
	s_barrier
; #define PG8_STAGE(bufoff, gbase, voff) do { _Pragma("unroll") for (int _i = 0; _i < 2; ++_i) \
;         __builtin_amdgcn_global_load_lds((const unsigned*)((const char*)(gbase) + (voff)[_i]), (PG8_LAS unsigned*)(lds + (bufoff) + ldsw + _i * 8192), 16, 0, 0); } while (0)
; #define PG8_LDA(dst, b, h) do { _Pragma("unroll") for (int m = 0; m < 4; ++m) _Pragma("unroll") for (int k = 0; k < 2; ++k) dst[m][k] = *(const PG8_LAS frag_t*)(lds + PG8_SA(b, h) + aoff + m * 2048 + k * 1024); } while (0)
; #define PG8_LDB(dst, b, h) do { _Pragma("unroll") for (int n = 0; n < 2; ++n) _Pragma("unroll") for (int k = 0; k < 2; ++k) dst[n][k] = *(const PG8_LAS frag_t*)(lds + PG8_SB(b, h) + boff + n * 2048 + k * 1024); } while (0)
; #define PG8_MMA(ai, bj, At, Bt) do { __builtin_amdgcn_s_setprio(1); _Pragma("unroll") for (int m = 0; m < 4; ++m) _Pragma("unroll") for (int n = 0; n < 2; ++n) _Pragma("unroll") for (int k = 0; k < 2; ++k) \
;         acc[ai][bj][m][n] = mma1v<MMAV>(Bt[n][k], At[m][k], acc[ai][bj][m][n]); __builtin_amdgcn_s_setprio(0); } while (0)
; #define PG8_WAIT_V(n) asm volatile("s_waitcnt vmcnt(" #n ")" ::: "memory")
; #define PG8_WAIT_L(n) asm volatile("s_waitcnt lgkmcnt(" #n ")" ::: "memory")
; #define PG8_BAR __builtin_amdgcn_s_barrier()
; #define PG8_SCHED __builtin_amdgcn_sched_barrier(0)
;     ...
;             PG8_WAIT_V(8); PG8_WAIT_L(0); PG8_BAR; PG8_MMA(1, 0, At, B0); PG8_MMA(1, 1, At, B1); PG8_BAR; PG8_SCHED;
;             PG8_LDB(B0, 1, 0); PG8_LDB(B1, 1, 1); PG8_SCHED; PG8_LDA(At, 1, 0); PG8_STAGE(PG8_SA(0, 1), a2 + hstep, voffA);
;             PG8_WAIT_V(8); PG8_WAIT_L(0); PG8_BAR; PG8_MMA(0, 0, At, B0); PG8_MMA(0, 1, At, B1); PG8_BAR; PG8_SCHED;
;             PG8_LDA(At, 1, 1); PG8_STAGE(PG8_SB(1, 0), b3, voffB); PG8_STAGE(PG8_SB(1, 1), b3 + hstepB, voffB); PG8_STAGE(PG8_SA(1, 0), a3, voffA);
;             PG8_WAIT_V(8); PG8_WAIT_L(0); PG8_BAR; PG8_MMA(1, 0, At, B0); PG8_MMA(1, 1, At, B1); PG8_BAR; PG8_SCHED;
	s_setprio 1
	s_waitcnt lgkmcnt(0)
	v_mfma_f32_16x16x32_bf16 v[62:65], v[130:133], v[216:219], 0
	v_mfma_f32_16x16x32_bf16 v[58:61], v[154:157], v[216:219], 0
	v_mfma_f32_16x16x32_bf16 v[46:49], v[130:133], v[224:227], 0
	v_mfma_f32_16x16x32_bf16 v[42:45], v[154:157], v[224:227], 0
	v_mfma_f32_16x16x32_bf16 v[30:33], v[130:133], v[232:235], 0
	v_mfma_f32_16x16x32_bf16 v[26:29], v[154:157], v[232:235], 0
	v_mfma_f32_16x16x32_bf16 v[14:17], v[130:133], v[240:243], 0
	v_mfma_f32_16x16x32_bf16 v[10:13], v[154:157], v[240:243], 0
	v_mfma_f32_16x16x32_bf16 v[62:65], v[134:137], v[220:223], v[62:65]
	v_mfma_f32_16x16x32_bf16 v[58:61], v[158:161], v[220:223], v[58:61]
	v_mfma_f32_16x16x32_bf16 v[46:49], v[134:137], v[228:231], v[46:49]
	v_mfma_f32_16x16x32_bf16 v[42:45], v[158:161], v[228:231], v[42:45]
	v_mfma_f32_16x16x32_bf16 v[30:33], v[134:137], v[236:239], v[30:33]
	v_mfma_f32_16x16x32_bf16 v[26:29], v[158:161], v[236:239], v[26:29]
	v_mfma_f32_16x16x32_bf16 v[14:17], v[134:137], v[244:247], v[14:17]
	v_mfma_f32_16x16x32_bf16 v[10:13], v[158:161], v[244:247], v[10:13]
	s_setprio 0
	s_setprio 1
	v_mfma_f32_16x16x32_bf16 v[54:57], v[174:177], v[216:219], 0
	v_mfma_f32_16x16x32_bf16 v[50:53], v[182:185], v[216:219], 0
	v_mfma_f32_16x16x32_bf16 v[38:41], v[174:177], v[224:227], 0
	v_mfma_f32_16x16x32_bf16 v[34:37], v[182:185], v[224:227], 0
	v_mfma_f32_16x16x32_bf16 v[22:25], v[174:177], v[232:235], 0
	v_mfma_f32_16x16x32_bf16 v[18:21], v[182:185], v[232:235], 0
	v_mfma_f32_16x16x32_bf16 v[6:9], v[174:177], v[240:243], 0
	v_mfma_f32_16x16x32_bf16 v[2:5], v[182:185], v[240:243], 0
	v_mfma_f32_16x16x32_bf16 v[54:57], v[178:181], v[220:223], v[54:57]
	v_mfma_f32_16x16x32_bf16 v[50:53], v[186:189], v[220:223], v[50:53]
	v_mfma_f32_16x16x32_bf16 v[38:41], v[178:181], v[228:231], v[38:41]
	v_mfma_f32_16x16x32_bf16 v[34:37], v[186:189], v[228:231], v[34:37]
	v_mfma_f32_16x16x32_bf16 v[22:25], v[178:181], v[236:239], v[22:25]
	v_mfma_f32_16x16x32_bf16 v[18:21], v[186:189], v[236:239], v[18:21]
	v_mfma_f32_16x16x32_bf16 v[6:9], v[178:181], v[244:247], v[6:9]
	v_mfma_f32_16x16x32_bf16 v[2:5], v[186:189], v[244:247], v[2:5]
	s_setprio 0
	s_barrier
	s_add_i32 s52, 0, 0x18000
	v_add_u32_e32 v148, s52, v151
	s_add_i32 s53, 0, 0x1c000
	ds_read_b128 v[130:133], v148
	ds_read_b128 v[134:137], v148 offset:1024
	ds_read_b128 v[154:157], v148 offset:2048
	ds_read_b128 v[158:161], v148 offset:3072
	v_add_u32_e32 v148, s53, v151
	ds_read_b128 v[174:177], v148
	ds_read_b128 v[178:181], v148 offset:1024
	ds_read_b128 v[182:185], v148 offset:2048
	ds_read_b128 v[186:189], v148 offset:3072
	s_add_u32 s22, s22, 0x4000
	s_addc_u32 s23, s23, 0
	s_mov_b32 m0, s35
	v_lshl_add_u64 v[148:149], s[22:23], 0, v[138:139]
	ds_read_b128 v[216:219], v152 offset:32768
	ds_read_b128 v[220:223], v152 offset:33792
	ds_read_b128 v[224:227], v152 offset:34816
	ds_read_b128 v[228:231], v152 offset:35840
	ds_read_b128 v[232:235], v152 offset:36864
	ds_read_b128 v[236:239], v152 offset:37888
	ds_read_b128 v[240:243], v152 offset:38912
	ds_read_b128 v[244:247], v152 offset:39936
	global_load_lds_dwordx4 v[148:149], off
	v_lshl_add_u64 v[148:149], s[22:23], 0, v[140:141]
	s_mov_b32 m0, s36
	s_nop 0
	global_load_lds_dwordx4 v[148:149], off
	s_waitcnt vmcnt(8)
	s_waitcnt lgkmcnt(0)
	s_barrier
	s_setprio 1
	s_waitcnt lgkmcnt(0)
	v_mfma_f32_16x16x32_bf16 v[126:129], v[130:133], v[216:219], v[126:129]
	v_mfma_f32_16x16x32_bf16 v[122:125], v[154:157], v[216:219], v[122:125]
	v_mfma_f32_16x16x32_bf16 v[110:113], v[130:133], v[224:227], v[110:113]
	v_mfma_f32_16x16x32_bf16 v[106:109], v[154:157], v[224:227], v[106:109]
	v_mfma_f32_16x16x32_bf16 v[94:97], v[130:133], v[232:235], v[94:97]
	v_mfma_f32_16x16x32_bf16 v[90:93], v[154:157], v[232:235], v[90:93]
	v_mfma_f32_16x16x32_bf16 v[78:81], v[130:133], v[240:243], v[78:81]
	v_mfma_f32_16x16x32_bf16 v[74:77], v[154:157], v[240:243], v[74:77]
	v_mfma_f32_16x16x32_bf16 v[126:129], v[134:137], v[220:223], v[126:129]
	v_mfma_f32_16x16x32_bf16 v[122:125], v[158:161], v[220:223], v[122:125]
	v_mfma_f32_16x16x32_bf16 v[110:113], v[134:137], v[228:231], v[110:113]
	v_mfma_f32_16x16x32_bf16 v[106:109], v[158:161], v[228:231], v[106:109]
	v_mfma_f32_16x16x32_bf16 v[94:97], v[134:137], v[236:239], v[94:97]
	v_mfma_f32_16x16x32_bf16 v[90:93], v[158:161], v[236:239], v[90:93]
	v_mfma_f32_16x16x32_bf16 v[78:81], v[134:137], v[244:247], v[78:81]
	v_mfma_f32_16x16x32_bf16 v[74:77], v[158:161], v[244:247], v[74:77]
	s_setprio 0
	s_setprio 1
	v_mfma_f32_16x16x32_bf16 v[118:121], v[174:177], v[216:219], v[118:121]
	v_mfma_f32_16x16x32_bf16 v[114:117], v[182:185], v[216:219], v[114:117]
	v_mfma_f32_16x16x32_bf16 v[102:105], v[174:177], v[224:227], v[102:105]
	v_mfma_f32_16x16x32_bf16 v[98:101], v[182:185], v[224:227], v[98:101]
	v_mfma_f32_16x16x32_bf16 v[86:89], v[174:177], v[232:235], v[86:89]
	v_mfma_f32_16x16x32_bf16 v[82:85], v[182:185], v[232:235], v[82:85]
	v_mfma_f32_16x16x32_bf16 v[70:73], v[174:177], v[240:243], v[70:73]
	v_mfma_f32_16x16x32_bf16 v[66:69], v[182:185], v[240:243], v[66:69]
	v_mfma_f32_16x16x32_bf16 v[118:121], v[178:181], v[220:223], v[118:121]
	v_mfma_f32_16x16x32_bf16 v[114:117], v[186:189], v[220:223], v[114:117]
	v_mfma_f32_16x16x32_bf16 v[102:105], v[178:181], v[228:231], v[102:105]
	v_mfma_f32_16x16x32_bf16 v[98:101], v[186:189], v[228:231], v[98:101]
	v_mfma_f32_16x16x32_bf16 v[86:89], v[178:181], v[236:239], v[86:89]
	v_mfma_f32_16x16x32_bf16 v[82:85], v[186:189], v[236:239], v[82:85]
	v_mfma_f32_16x16x32_bf16 v[70:73], v[178:181], v[244:247], v[70:73]
	v_mfma_f32_16x16x32_bf16 v[66:69], v[186:189], v[244:247], v[66:69]
	s_setprio 0
	s_barrier
; #define PG8_STAGE(bufoff, gbase, voff) do { _Pragma("unroll") for (int _i = 0; _i < 2; ++_i) \
;         __builtin_amdgcn_global_load_lds((const unsigned*)((const char*)(gbase) + (voff)[_i]), (PG8_LAS unsigned*)(lds + (bufoff) + ldsw + _i * 8192), 16, 0, 0); } while (0)
; #define PG8_LDA(dst, b, h) do { _Pragma("unroll") for (int m = 0; m < 4; ++m) _Pragma("unroll") for (int k = 0; k < 2; ++k) dst[m][k] = *(const PG8_LAS frag_t*)(lds + PG8_SA(b, h) + aoff + m * 2048 + k * 1024); } while (0)
; #define PG8_MMA(ai, bj, At, Bt) do { __builtin_amdgcn_s_setprio(1); _Pragma("unroll") for (int m = 0; m < 4; ++m) _Pragma("unroll") for (int n = 0; n < 2; ++n) _Pragma("unroll") for (int k = 0; k < 2; ++k) \
;         acc[ai][bj][m][n] = mma1v<MMAV>(Bt[n][k], At[m][k], acc[ai][bj][m][n]); __builtin_amdgcn_s_setprio(0); } while (0)
; #define PG8_WAIT_V(n) asm volatile("s_waitcnt vmcnt(" #n ")" ::: "memory")
; #define PG8_WAIT_L(n) asm volatile("s_waitcnt lgkmcnt(" #n ")" ::: "memory")
; #define PG8_BAR __builtin_amdgcn_s_barrier()
; #define PG8_SCHED __builtin_amdgcn_sched_barrier(0)
;     ...
;             PG8_WAIT_V(8); PG8_WAIT_L(0); PG8_BAR; PG8_MMA(0, 0, At, B0); PG8_MMA(0, 1, At, B1); PG8_BAR; PG8_SCHED;
;             PG8_LDA(At, 1, 1); PG8_STAGE(PG8_SB(1, 0), b3, voffB); PG8_STAGE(PG8_SB(1, 1), b3 + hstepB, voffB); PG8_STAGE(PG8_SA(1, 0), a3, voffA);
;             PG8_WAIT_V(8); PG8_WAIT_L(0); PG8_BAR; PG8_MMA(1, 0, At, B0); PG8_MMA(1, 1, At, B1); PG8_BAR; PG8_SCHED;
	s_add_u32 s22, s20, 0x8000
	s_addc_u32 s23, s21, 0
	s_add_i32 s52, s52, s30
	v_lshl_add_u64 v[148:149], s[22:23], 0, v[162:163]
	s_mov_b32 m0, s52
	ds_read_b128 v[216:219], v152 offset:49152
	ds_read_b128 v[220:223], v152 offset:50176
	ds_read_b128 v[224:227], v152 offset:51200
	ds_read_b128 v[228:231], v152 offset:52224
	ds_read_b128 v[232:235], v152 offset:53248
	ds_read_b128 v[236:239], v152 offset:54272
	ds_read_b128 v[240:243], v152 offset:55296
	ds_read_b128 v[244:247], v152 offset:56320
	global_load_lds_dwordx4 v[148:149], off
	s_add_i32 m0, s52, 0x2000
	s_add_u32 s20, s20, 0xc000
	v_lshl_add_u64 v[148:149], s[22:23], 0, v[142:143]
	s_addc_u32 s21, s21, 0
	s_add_i32 s22, s53, s30
	global_load_lds_dwordx4 v[148:149], off
	v_lshl_add_u64 v[148:149], s[20:21], 0, v[162:163]
	s_mov_b32 m0, s22
	s_nop 0
	global_load_lds_dwordx4 v[148:149], off
	v_lshl_add_u64 v[148:149], s[20:21], 0, v[142:143]
	s_add_i32 m0, s22, 0x2000
	s_nop 0
	global_load_lds_dwordx4 v[148:149], off
	v_lshl_add_u64 v[148:149], s[18:19], 0, v[138:139]
	s_mov_b32 m0, s40
	s_nop 0
	global_load_lds_dwordx4 v[148:149], off
	v_lshl_add_u64 v[148:149], s[18:19], 0, v[140:141]
	s_mov_b32 m0, s41
	s_nop 0
	global_load_lds_dwordx4 v[148:149], off
	s_waitcnt vmcnt(8)
	s_waitcnt lgkmcnt(0)
	s_barrier
	s_setprio 1
	s_waitcnt lgkmcnt(0)
	v_mfma_f32_16x16x32_bf16 v[62:65], v[130:133], v[216:219], v[62:65]
	v_mfma_f32_16x16x32_bf16 v[58:61], v[154:157], v[216:219], v[58:61]
	v_mfma_f32_16x16x32_bf16 v[46:49], v[130:133], v[224:227], v[46:49]
	v_mfma_f32_16x16x32_bf16 v[42:45], v[154:157], v[224:227], v[42:45]
	v_mfma_f32_16x16x32_bf16 v[30:33], v[130:133], v[232:235], v[30:33]
	v_mfma_f32_16x16x32_bf16 v[26:29], v[154:157], v[232:235], v[26:29]
	v_mfma_f32_16x16x32_bf16 v[14:17], v[130:133], v[240:243], v[14:17]
	v_mfma_f32_16x16x32_bf16 v[10:13], v[154:157], v[240:243], v[10:13]
	v_mfma_f32_16x16x32_bf16 v[62:65], v[134:137], v[220:223], v[62:65]
	v_mfma_f32_16x16x32_bf16 v[58:61], v[158:161], v[220:223], v[58:61]
	v_mfma_f32_16x16x32_bf16 v[46:49], v[134:137], v[228:231], v[46:49]
	v_mfma_f32_16x16x32_bf16 v[42:45], v[158:161], v[228:231], v[42:45]
	v_mfma_f32_16x16x32_bf16 v[30:33], v[134:137], v[236:239], v[30:33]
	v_mfma_f32_16x16x32_bf16 v[26:29], v[158:161], v[236:239], v[26:29]
	v_mfma_f32_16x16x32_bf16 v[14:17], v[134:137], v[244:247], v[14:17]
	v_mfma_f32_16x16x32_bf16 v[10:13], v[158:161], v[244:247], v[10:13]
	s_setprio 0
	s_setprio 1
	v_mfma_f32_16x16x32_bf16 v[54:57], v[174:177], v[216:219], v[54:57]
	v_mfma_f32_16x16x32_bf16 v[50:53], v[182:185], v[216:219], v[50:53]
	v_mfma_f32_16x16x32_bf16 v[38:41], v[174:177], v[224:227], v[38:41]
	v_mfma_f32_16x16x32_bf16 v[34:37], v[182:185], v[224:227], v[34:37]
	v_mfma_f32_16x16x32_bf16 v[22:25], v[174:177], v[232:235], v[22:25]
	v_mfma_f32_16x16x32_bf16 v[18:21], v[182:185], v[232:235], v[18:21]
	v_mfma_f32_16x16x32_bf16 v[6:9], v[174:177], v[240:243], v[6:9]
	v_mfma_f32_16x16x32_bf16 v[2:5], v[182:185], v[240:243], v[2:5]
	v_mfma_f32_16x16x32_bf16 v[54:57], v[178:181], v[220:223], v[54:57]
	v_mfma_f32_16x16x32_bf16 v[50:53], v[186:189], v[220:223], v[50:53]
	v_mfma_f32_16x16x32_bf16 v[38:41], v[178:181], v[228:231], v[38:41]
	v_mfma_f32_16x16x32_bf16 v[34:37], v[186:189], v[228:231], v[34:37]
	v_mfma_f32_16x16x32_bf16 v[22:25], v[178:181], v[236:239], v[22:25]
	v_mfma_f32_16x16x32_bf16 v[18:21], v[186:189], v[236:239], v[18:21]
	v_mfma_f32_16x16x32_bf16 v[6:9], v[178:181], v[244:247], v[6:9]
	v_mfma_f32_16x16x32_bf16 v[2:5], v[186:189], v[244:247], v[2:5]
	s_setprio 0
	s_barrier
	s_add_i32 s51, s51, 2
	s_add_u32 s6, s6, 0x10000
	s_addc_u32 s7, s7, 0
	s_add_u32 s49, s49, 0x10000
	s_addc_u32 s50, s50, 0
